# gemm256 K-loop variant: LDS-DMA issue moved earlier (G0-G2), address math at loop top
# baseline (speedup 1.0000x reference)
; #define GLDS_STAGE(st, kt_) do { \
;         _Pragma("unroll") for (int i_ = 0; i_ < FI; ++i_) { \
;             glds16(ap + (size_t)(32 * i_) * lda + (kt_) * 64, l3a + (st) + tid * 16 + i_ * 4096); \
;             glds16(bp + (size_t)(32 * i_) * ldb + (kt_) * 64, l3a + (st) + OPB + tid * 16 + i_ * 4096); } } while (0)
; #define GLDS_STAGE(st, kt_) do { \
;         _Pragma("unroll") for (int i_ = 0; i_ < 4; ++i_) { \
;             glds16(ap + (size_t)(64 * i_) * lda + (kt_) * 64, l3a + (st) + tid * 16 + i_ * 8192); \
;             glds16(bp + (size_t)(64 * i_) * ldb + (kt_) * 64, l3a + (st) + 32768 + tid * 16 + i_ * 8192); } } while (0)
; template <class Epi>
; DEV void gemm256_tile(const bf16_t* __restrict__ A, int lda, const bf16_t* __restrict__ Bt, int ldb, int K, unsigned char* lds, const Epi& epi) {
;     ...
;     GLDS_STAGE(0, 0);
;     const int aoff = (wr * 128 + fr) * 128, boff = 32768 + (wc * 64 + fr) * 128, sw = fr & 7;
;     for (int kt = 0; kt < nk; ++kt) {
;         const int cur = (kt & 1) * 65536;
;         asm volatile("s_waitcnt vmcnt(0)" ::: "memory");
;         __syncthreads();
;         if (kt + 1 < nk) GLDS_STAGE(cur ^ 65536, kt + 1);
; #pragma unroll
;         for (int kh = 0; kh < 2; ++kh) {
;             bf16x8 bfr[4];
;             const int ch = ((kh * 4 + fq) ^ sw) << 4;
; #pragma unroll
;             for (int i = 0; i < 4; ++i) bfr[i] = *(const bf16x8*)(lds + cur + boff + i * 2048 + ch);
; #pragma unroll
;             for (int mh = 0; mh < 2; ++mh) {
;                 bf16x8 af[4];
; #pragma unroll
;                 for (int i = 0; i < 4; ++i) af[i] = *(const bf16x8*)(lds + cur + aoff + (mh * 4 + i) * 2048 + ch);
; #pragma unroll
;                 for (int mi = 0; mi < 4; ++mi)
; #pragma unroll
;                     for (int ni = 0; ni < 4; ++ni) acc[mh * 4 + mi][ni] = __builtin_amdgcn_mfma_f32_16x16x32_bf16(bfr[ni], af[mi], acc[mh * 4 + mi][ni], 0, 0, 0);
.LBB0_174:
	s_and_b32 s48, s21, 0x10000
	s_xor_b32 s49, s48, 0x10000
	v_add_u32_e32 v216, s49, v142
	v_add_u32_e32 v217, s49, v156
	s_waitcnt vmcnt(0) lgkmcnt(0)
	s_barrier
	v_or_b32_e32 v248, s48, v175
	v_add_u32_e32 v249, s48, v157
	v_add_u32_e32 v244, v248, v174
	v_add_u32_e32 v245, v249, v174
	ds_read_b128 v[176:179], v244 offset:32768
	ds_read_b128 v[180:183], v244 offset:34816
	ds_read_b128 v[184:187], v244 offset:36864
	ds_read_b128 v[188:191], v244 offset:38912
	ds_read_b128 v[228:231], v245
	ds_read_b128 v[232:235], v245 offset:2048
	ds_read_b128 v[236:239], v245 offset:4096
	ds_read_b128 v[240:243], v245 offset:6144
	v_readfirstlane_b32 s40, v216
	v_readfirstlane_b32 s44, v217
	v_add_u32_e32 v246, v248, v155
	v_add_u32_e32 v247, v249, v155
	s_mov_b32 m0, s40
	v_lshl_add_u64 v[204:205], v[144:145], 0, s[4:5]
	global_load_lds_dwordx4 v[144:145], off
	s_mov_b32 m0, s44
	v_lshl_add_u64 v[210:211], v[146:147], 0, s[4:5]
	global_load_lds_dwordx4 v[146:147], off
	s_add_i32 s41, s40, 0x2000
	s_add_i32 s45, s44, 0x2000
	s_add_i32 s42, s40, 0x4000
	s_add_i32 s46, s44, 0x4000
	s_add_i32 s43, s40, 0x6000
	s_add_i32 s47, s44, 0x6000
	s_add_i32 s21, s21, 0x10000
	v_lshl_add_u64 v[206:207], v[144:145], 0, s[6:7]
	v_lshl_add_u64 v[212:213], v[146:147], 0, s[6:7]
	v_lshl_add_u64 v[208:209], v[144:145], 0, s[8:9]
	v_lshl_add_u64 v[214:215], v[146:147], 0, s[8:9]
	s_waitcnt lgkmcnt(3)
	v_mfma_f32_16x16x32_bf16 v[126:129], v[176:179], v[228:231], v[126:129]
	s_mov_b32 m0, s41
	v_mfma_f32_16x16x32_bf16 v[122:125], v[180:183], v[228:231], v[122:125]
	global_load_lds_dwordx4 v[204:205], off
	v_mfma_f32_16x16x32_bf16 v[118:121], v[184:187], v[228:231], v[118:121]
	s_mov_b32 m0, s45
	v_mfma_f32_16x16x32_bf16 v[114:117], v[188:191], v[228:231], v[114:117]
	global_load_lds_dwordx4 v[210:211], off
	s_waitcnt lgkmcnt(2)
	v_mfma_f32_16x16x32_bf16 v[110:113], v[176:179], v[232:235], v[110:113]
	v_mfma_f32_16x16x32_bf16 v[106:109], v[180:183], v[232:235], v[106:109]
	v_mfma_f32_16x16x32_bf16 v[102:105], v[184:187], v[232:235], v[102:105]
	v_mfma_f32_16x16x32_bf16 v[98:101], v[188:191], v[232:235], v[98:101]
	s_waitcnt lgkmcnt(1)
	v_mfma_f32_16x16x32_bf16 v[94:97], v[176:179], v[236:239], v[94:97]
	ds_read_b128 v[228:231], v245 offset:8192
	v_mfma_f32_16x16x32_bf16 v[90:93], v[180:183], v[236:239], v[90:93]
	ds_read_b128 v[232:235], v245 offset:10240
	v_mfma_f32_16x16x32_bf16 v[86:89], v[184:187], v[236:239], v[86:89]
	s_mov_b32 m0, s42
	v_mfma_f32_16x16x32_bf16 v[82:85], v[188:191], v[236:239], v[82:85]
	global_load_lds_dwordx4 v[206:207], off
	s_waitcnt lgkmcnt(2)
	v_mfma_f32_16x16x32_bf16 v[78:81], v[176:179], v[240:243], v[78:81]
	s_mov_b32 m0, s46
	v_mfma_f32_16x16x32_bf16 v[74:77], v[180:183], v[240:243], v[74:77]
	global_load_lds_dwordx4 v[212:213], off
	v_mfma_f32_16x16x32_bf16 v[70:73], v[184:187], v[240:243], v[70:73]
	v_mfma_f32_16x16x32_bf16 v[66:69], v[188:191], v[240:243], v[66:69]
	s_waitcnt lgkmcnt(1)
	v_mfma_f32_16x16x32_bf16 v[62:65], v[176:179], v[228:231], v[62:65]
	ds_read_b128 v[236:239], v245 offset:12288
	v_mfma_f32_16x16x32_bf16 v[58:61], v[180:183], v[228:231], v[58:61]
	ds_read_b128 v[240:243], v245 offset:14336
	v_mfma_f32_16x16x32_bf16 v[54:57], v[184:187], v[228:231], v[54:57]
	s_mov_b32 m0, s43
	v_mfma_f32_16x16x32_bf16 v[50:53], v[188:191], v[228:231], v[50:53]
	global_load_lds_dwordx4 v[208:209], off
	s_waitcnt lgkmcnt(2)
	v_mfma_f32_16x16x32_bf16 v[46:49], v[176:179], v[232:235], v[46:49]
	s_mov_b32 m0, s47
	v_mfma_f32_16x16x32_bf16 v[42:45], v[180:183], v[232:235], v[42:45]
	global_load_lds_dwordx4 v[214:215], off
	v_mfma_f32_16x16x32_bf16 v[34:37], v[184:187], v[232:235], v[34:37]
	v_lshl_add_u64 v[144:145], v[144:145], 0, s[10:11]
	v_mfma_f32_16x16x32_bf16 v[30:33], v[188:191], v[232:235], v[30:33]
	v_lshl_add_u64 v[146:147], v[146:147], 0, s[10:11]
	s_waitcnt lgkmcnt(1)
	v_mfma_f32_16x16x32_bf16 v[26:29], v[176:179], v[236:239], v[26:29]
	ds_read_b128 v[192:195], v246 offset:32768
	v_mfma_f32_16x16x32_bf16 v[22:25], v[180:183], v[236:239], v[22:25]
	ds_read_b128 v[196:199], v246 offset:34816
	v_mfma_f32_16x16x32_bf16 v[18:21], v[184:187], v[236:239], v[18:21]
	ds_read_b128 v[220:223], v246 offset:36864
	v_mfma_f32_16x16x32_bf16 v[14:17], v[188:191], v[236:239], v[14:17]
	ds_read_b128 v[224:227], v246 offset:38912
	s_waitcnt lgkmcnt(4)
	v_mfma_f32_16x16x32_bf16 v[10:13], v[176:179], v[240:243], v[10:13]
	ds_read_b128 v[228:231], v247
	v_mfma_f32_16x16x32_bf16 v[6:9], v[180:183], v[240:243], v[6:9]
	ds_read_b128 v[232:235], v247 offset:2048
	v_mfma_f32_16x16x32_bf16 v[2:5], v[184:187], v[240:243], v[2:5]
	v_mfma_f32_16x16x32_bf16 v[38:41], v[188:191], v[240:243], v[38:41]
	s_waitcnt lgkmcnt(1)
	v_mfma_f32_16x16x32_bf16 v[126:129], v[192:195], v[228:231], v[126:129]
	ds_read_b128 v[236:239], v247 offset:4096
	v_mfma_f32_16x16x32_bf16 v[122:125], v[196:199], v[228:231], v[122:125]
	ds_read_b128 v[240:243], v247 offset:6144
	v_mfma_f32_16x16x32_bf16 v[118:121], v[220:223], v[228:231], v[118:121]
	v_mfma_f32_16x16x32_bf16 v[114:117], v[224:227], v[228:231], v[114:117]
	s_waitcnt lgkmcnt(2)
	v_mfma_f32_16x16x32_bf16 v[110:113], v[192:195], v[232:235], v[110:113]
	v_mfma_f32_16x16x32_bf16 v[106:109], v[196:199], v[232:235], v[106:109]
	v_mfma_f32_16x16x32_bf16 v[102:105], v[220:223], v[232:235], v[102:105]
	v_mfma_f32_16x16x32_bf16 v[98:101], v[224:227], v[232:235], v[98:101]
	s_waitcnt lgkmcnt(1)
	v_mfma_f32_16x16x32_bf16 v[94:97], v[192:195], v[236:239], v[94:97]
	ds_read_b128 v[228:231], v247 offset:8192
	v_mfma_f32_16x16x32_bf16 v[90:93], v[196:199], v[236:239], v[90:93]
	ds_read_b128 v[232:235], v247 offset:10240
	v_mfma_f32_16x16x32_bf16 v[86:89], v[220:223], v[236:239], v[86:89]
	v_mfma_f32_16x16x32_bf16 v[82:85], v[224:227], v[236:239], v[82:85]
	s_waitcnt lgkmcnt(2)
; DEV unsigned cvt_pk_bf16(float lo, float hi) { const f32x2_t v = {lo, hi}; const bf16x2_t b = __builtin_convertvector(v, bf16x2_t); return __builtin_bit_cast(unsigned, b); }
; #define GLDS_STAGE(st, kt_) do { \
;         _Pragma("unroll") for (int i_ = 0; i_ < FI; ++i_) { \
;             glds16(ap + (size_t)(32 * i_) * lda + (kt_) * 64, l3a + (st) + tid * 16 + i_ * 4096); \
;             glds16(bp + (size_t)(32 * i_) * ldb + (kt_) * 64, l3a + (st) + OPB + tid * 16 + i_ * 4096); } } while (0)
; template <class Epi>
; DEV void gemm256_tile(const bf16_t* __restrict__ A, int lda, const bf16_t* __restrict__ Bt, int ldb, int K, unsigned char* lds, const Epi& epi) {
;     ...
;     for (int kt = 0; kt < nk; ++kt) {
;         const int cur = (kt & 1) * 65536;
;         asm volatile("s_waitcnt vmcnt(0)" ::: "memory");
;         __syncthreads();
;         if (kt + 1 < nk) GLDS_STAGE(cur ^ 65536, kt + 1);
; #pragma unroll
;         for (int kh = 0; kh < 2; ++kh) {
;             bf16x8 bfr[4];
;             const int ch = ((kh * 4 + fq) ^ sw) << 4;
; #pragma unroll
;             for (int i = 0; i < 4; ++i) bfr[i] = *(const bf16x8*)(lds + cur + boff + i * 2048 + ch);
; #pragma unroll
;             for (int mh = 0; mh < 2; ++mh) {
;                 bf16x8 af[4];
; #pragma unroll
;                 for (int i = 0; i < 4; ++i) af[i] = *(const bf16x8*)(lds + cur + aoff + (mh * 4 + i) * 2048 + ch);
; #pragma unroll
;                 for (int mi = 0; mi < 4; ++mi)
; #pragma unroll
;                     for (int ni = 0; ni < 4; ++ni) acc[mh * 4 + mi][ni] = __builtin_amdgcn_mfma_f32_16x16x32_bf16(bfr[ni], af[mi], acc[mh * 4 + mi][ni], 0, 0, 0);
;             }
;         }
;     }
;     ...
;     __syncthreads();
;     if constexpr (Epi::STAGE) {
; #pragma unroll
;         for (int mi = 0; mi < 8; ++mi)
; #pragma unroll
;             for (int ni = 0; ni < 4; ++ni) {
;                 const int row = wr * 128 + mi * 16 + fr, col = wc * 64 + ni * 16 + fq * 4;
;                 const f32x4 v = epi.xform(row, col, acc[mi][ni]);
;                 uint2 w; w.x = cvt_pk_bf16(v[0], v[1]); w.y = cvt_pk_bf16(v[2], v[3]);
;                 *(uint2*)(lds + row * 512 + ((((col >> 3) ^ (row & 31)) << 4) | (((col >> 2) & 1) << 3))) = w;
	v_mfma_f32_16x16x32_bf16 v[78:81], v[192:195], v[240:243], v[78:81]
	v_mfma_f32_16x16x32_bf16 v[74:77], v[196:199], v[240:243], v[74:77]
	v_mfma_f32_16x16x32_bf16 v[70:73], v[220:223], v[240:243], v[70:73]
	v_mfma_f32_16x16x32_bf16 v[66:69], v[224:227], v[240:243], v[66:69]
	s_waitcnt lgkmcnt(1)
	v_mfma_f32_16x16x32_bf16 v[62:65], v[192:195], v[228:231], v[62:65]
	ds_read_b128 v[236:239], v247 offset:12288
	v_mfma_f32_16x16x32_bf16 v[58:61], v[196:199], v[228:231], v[58:61]
	ds_read_b128 v[240:243], v247 offset:14336
	v_mfma_f32_16x16x32_bf16 v[54:57], v[220:223], v[228:231], v[54:57]
	v_mfma_f32_16x16x32_bf16 v[50:53], v[224:227], v[228:231], v[50:53]
	s_waitcnt lgkmcnt(2)
	v_mfma_f32_16x16x32_bf16 v[46:49], v[192:195], v[232:235], v[46:49]
	v_mfma_f32_16x16x32_bf16 v[42:45], v[196:199], v[232:235], v[42:45]
	v_mfma_f32_16x16x32_bf16 v[34:37], v[220:223], v[232:235], v[34:37]
	v_mfma_f32_16x16x32_bf16 v[30:33], v[224:227], v[232:235], v[30:33]
	s_waitcnt lgkmcnt(1)
	v_mfma_f32_16x16x32_bf16 v[26:29], v[192:195], v[236:239], v[26:29]
	v_mfma_f32_16x16x32_bf16 v[22:25], v[196:199], v[236:239], v[22:25]
	v_mfma_f32_16x16x32_bf16 v[18:21], v[220:223], v[236:239], v[18:21]
	v_mfma_f32_16x16x32_bf16 v[14:17], v[224:227], v[236:239], v[14:17]
	s_waitcnt lgkmcnt(0)
	v_mfma_f32_16x16x32_bf16 v[10:13], v[192:195], v[240:243], v[10:13]
	v_mfma_f32_16x16x32_bf16 v[6:9], v[196:199], v[240:243], v[6:9]
	v_mfma_f32_16x16x32_bf16 v[2:5], v[220:223], v[240:243], v[2:5]
	v_mfma_f32_16x16x32_bf16 v[38:41], v[224:227], v[240:243], v[38:41]
	s_cmp_eq_u32 s21, 0x1f0000
	s_cbranch_scc0 .LBB0_174
	v_or_b32_e32 v156, 0x18000, v175
	v_add_u32_e32 v157, 0x10000, v157
	v_add_u32_e32 v186, v156, v174
	v_add_u32_e32 v194, v157, v174
	s_waitcnt vmcnt(0)
	s_barrier
	ds_read_b128 v[144:147], v186
	ds_read_b128 v[178:181], v186 offset:2048
	ds_read_b128 v[174:177], v194
	ds_read_b128 v[182:185], v186 offset:4096
	ds_read_b128 v[186:189], v186 offset:6144
	s_waitcnt lgkmcnt(2)
	v_mfma_f32_16x16x32_bf16 v[126:129], v[144:147], v[174:177], v[126:129]
	s_sext_i32_i16 s20, s20
	s_lshl_b32 s20, s20, 8
	s_ashr_i32 s21, s20, 31
	v_mfma_f32_16x16x32_bf16 v[122:125], v[178:181], v[174:177], v[122:125]
	s_waitcnt lgkmcnt(1)
	v_mfma_f32_16x16x32_bf16 v[118:121], v[182:185], v[174:177], v[118:121]
	s_waitcnt lgkmcnt(0)
	v_mfma_f32_16x16x32_bf16 v[114:117], v[186:189], v[174:177], v[114:117]
	ds_read_b128 v[174:177], v194 offset:2048
	s_waitcnt lgkmcnt(0)
	v_mfma_f32_16x16x32_bf16 v[110:113], v[144:147], v[174:177], v[110:113]
	v_mfma_f32_16x16x32_bf16 v[106:109], v[178:181], v[174:177], v[106:109]
	v_mfma_f32_16x16x32_bf16 v[102:105], v[182:185], v[174:177], v[102:105]
	v_mfma_f32_16x16x32_bf16 v[98:101], v[186:189], v[174:177], v[98:101]
	ds_read_b128 v[174:177], v194 offset:4096
	s_waitcnt lgkmcnt(0)
	v_mfma_f32_16x16x32_bf16 v[94:97], v[144:147], v[174:177], v[94:97]
	v_mfma_f32_16x16x32_bf16 v[90:93], v[178:181], v[174:177], v[90:93]
	v_mfma_f32_16x16x32_bf16 v[86:89], v[182:185], v[174:177], v[86:89]
	v_mfma_f32_16x16x32_bf16 v[82:85], v[186:189], v[174:177], v[82:85]
	ds_read_b128 v[174:177], v194 offset:6144
	s_waitcnt lgkmcnt(0)
	v_mfma_f32_16x16x32_bf16 v[78:81], v[144:147], v[174:177], v[78:81]
	v_mfma_f32_16x16x32_bf16 v[74:77], v[178:181], v[174:177], v[74:77]
	v_mfma_f32_16x16x32_bf16 v[70:73], v[182:185], v[174:177], v[70:73]
	v_mfma_f32_16x16x32_bf16 v[66:69], v[186:189], v[174:177], v[66:69]
	ds_read_b128 v[174:177], v194 offset:8192
	ds_read_b128 v[190:193], v194 offset:10240
	s_waitcnt lgkmcnt(1)
	v_mfma_f32_16x16x32_bf16 v[62:65], v[144:147], v[174:177], v[62:65]
	v_mfma_f32_16x16x32_bf16 v[58:61], v[178:181], v[174:177], v[58:61]
	v_mfma_f32_16x16x32_bf16 v[54:57], v[182:185], v[174:177], v[54:57]
	v_mfma_f32_16x16x32_bf16 v[50:53], v[186:189], v[174:177], v[50:53]
	ds_read_b128 v[174:177], v194 offset:12288
	s_waitcnt lgkmcnt(1)
	v_mfma_f32_16x16x32_bf16 v[46:49], v[144:147], v[190:193], v[46:49]
	v_mfma_f32_16x16x32_bf16 v[42:45], v[178:181], v[190:193], v[42:45]
	v_mfma_f32_16x16x32_bf16 v[34:37], v[182:185], v[190:193], v[34:37]
	v_mfma_f32_16x16x32_bf16 v[30:33], v[186:189], v[190:193], v[30:33]
	ds_read_b128 v[190:193], v194 offset:14336
	s_waitcnt lgkmcnt(1)
	v_mfma_f32_16x16x32_bf16 v[194:197], v[144:147], v[174:177], v[26:29]
	s_nop 2
	v_add_u32_e32 v29, v156, v155
	ds_read_b128 v[198:201], v29
	ds_read_b128 v[202:205], v29 offset:2048
	ds_read_b128 v[206:209], v29 offset:4096
	ds_read_b128 v[210:213], v29 offset:6144
	v_add_u32_e32 v29, v157, v155
	v_mfma_f32_16x16x32_bf16 v[22:25], v[178:181], v[174:177], v[22:25]
	v_and_b32_e32 v28, 0xc0, v150
	v_lshl_or_b32 v153, v153, 2, v28
	v_lshlrev_b32_e32 v28, 3, v152
	v_mfma_f32_16x16x32_bf16 v[18:21], v[182:185], v[174:177], v[18:21]
	v_mad_i64_i32 v[26:27], s[22:23], s19, v149, v[172:173]
	v_lshl_add_u64 v[26:27], s[20:21], 1, v[26:27]
	v_mfma_f32_16x16x32_bf16 v[14:17], v[186:189], v[174:177], v[14:17]
	ds_read_b128 v[174:177], v29
	ds_read_b128 v[214:217], v29 offset:2048
	ds_read_b128 v[218:221], v29 offset:4096
	ds_read_b128 v[222:225], v29 offset:6144
	s_mov_b32 s19, 0
	s_waitcnt lgkmcnt(3)
	v_mfma_f32_16x16x32_bf16 v[126:129], v[198:201], v[174:177], v[126:129]
	v_mfma_f32_16x16x32_bf16 v[122:125], v[202:205], v[174:177], v[122:125]
	s_waitcnt lgkmcnt(1)
	v_mfma_f32_16x16x32_bf16 v[94:97], v[198:201], v[218:221], v[94:97]
	v_mfma_f32_16x16x32_bf16 v[10:13], v[144:147], v[190:193], v[10:13]
	ds_read_b128 v[144:147], v29 offset:8192
	ds_read_b128 v[226:229], v29 offset:10240
	ds_read_b128 v[230:233], v29 offset:12288
	ds_read_b128 v[234:237], v29 offset:14336
	v_lshlrev_b32_e32 v29, 9, v154
	v_and_or_b32 v152, v28, 8, v29
	v_mfma_f32_16x16x32_bf16 v[118:121], v[206:209], v[174:177], v[118:121]
	v_cvt_pk_bf16_f32 v28, v126, v127
	v_lshrrev_b32_e32 v126, 3, v153
	v_xor_b32_e32 v127, v126, v151
	v_mfma_f32_16x16x32_bf16 v[90:93], v[202:205], v[218:221], v[90:93]
	v_cvt_pk_bf16_f32 v29, v128, v129
	v_lshl_or_b32 v127, v127, 4, v152
	v_cvt_pk_bf16_f32 v122, v122, v123
	v_mfma_f32_16x16x32_bf16 v[114:117], v[210:213], v[174:177], v[114:117]
	v_cvt_pk_bf16_f32 v123, v124, v125
	v_bitop3_b32 v124, v126, v151, 2 bitop3:0x36
	v_cvt_pk_bf16_f32 v94, v94, v95
	v_mfma_f32_16x16x32_bf16 v[86:89], v[206:209], v[218:221], v[86:89]
	v_cvt_pk_bf16_f32 v95, v96, v97
	s_waitcnt lgkmcnt(0)
	s_barrier
; DEV unsigned cvt_pk_bf16(float lo, float hi) { const f32x2_t v = {lo, hi}; const bf16x2_t b = __builtin_convertvector(v, bf16x2_t); return __builtin_bit_cast(unsigned, b); }
; template <class Epi>
; DEV void gemm256_tile(const bf16_t* __restrict__ A, int lda, const bf16_t* __restrict__ Bt, int ldb, int K, unsigned char* lds, const Epi& epi) {
;     ...
;                 for (int mi = 0; mi < 4; ++mi)
; #pragma unroll
;                     for (int ni = 0; ni < 4; ++ni) acc[mh * 4 + mi][ni] = __builtin_amdgcn_mfma_f32_16x16x32_bf16(bfr[ni], af[mi], acc[mh * 4 + mi][ni], 0, 0, 0);
;             }
;         }
;     }
;     ...
;     __syncthreads();
;     if constexpr (Epi::STAGE) {
; #pragma unroll
;         for (int mi = 0; mi < 8; ++mi)
; #pragma unroll
;             for (int ni = 0; ni < 4; ++ni) {
;                 const int row = wr * 128 + mi * 16 + fr, col = wc * 64 + ni * 16 + fq * 4;
;                 const f32x4 v = epi.xform(row, col, acc[mi][ni]);
;                 uint2 w; w.x = cvt_pk_bf16(v[0], v[1]); w.y = cvt_pk_bf16(v[2], v[3]);
;                 *(uint2*)(lds + row * 512 + ((((col >> 3) ^ (row & 31)) << 4) | (((col >> 2) & 1) << 3))) = w;
;             }
;         __syncthreads();
	v_mfma_f32_16x16x32_bf16 v[110:113], v[198:201], v[214:217], v[110:113]
	v_lshl_add_u32 v124, v124, 4, v152
	v_cvt_pk_bf16_f32 v118, v118, v119
	v_mfma_f32_16x16x32_bf16 v[82:85], v[210:213], v[218:221], v[82:85]
	v_cvt_pk_bf16_f32 v119, v120, v121
	v_bitop3_b32 v120, v126, v151, 4 bitop3:0x36
	ds_write2st64_b64 v127, v[28:29], v[94:95] offset1:32
	v_mfma_f32_16x16x32_bf16 v[106:109], v[202:205], v[214:217], v[106:109]
	v_cvt_pk_bf16_f32 v28, v90, v91
	v_cvt_pk_bf16_f32 v29, v92, v93
	v_lshl_add_u32 v120, v120, 4, v152
	v_mfma_f32_16x16x32_bf16 v[78:81], v[198:201], v[222:225], v[78:81]
	v_cvt_pk_bf16_f32 v114, v114, v115
	v_cvt_pk_bf16_f32 v115, v116, v117
	v_bitop3_b32 v116, v126, v151, 6 bitop3:0x36
	v_mfma_f32_16x16x32_bf16 v[102:105], v[206:209], v[214:217], v[102:105]
	ds_write2st64_b64 v124, v[122:123], v[28:29] offset1:32
	v_cvt_pk_bf16_f32 v28, v86, v87
	v_cvt_pk_bf16_f32 v29, v88, v89
	v_mfma_f32_16x16x32_bf16 v[74:77], v[202:205], v[222:225], v[74:77]
	v_lshl_add_u32 v116, v116, 4, v152
	v_or_b32_e32 v117, 16, v151
	v_cvt_pk_bf16_f32 v110, v110, v111
	v_mfma_f32_16x16x32_bf16 v[2:5], v[182:185], v[190:193], v[2:5]
	v_cvt_pk_bf16_f32 v111, v112, v113
	v_bitop3_b32 v112, v126, v151, 16 bitop3:0x1e
	ds_write2st64_b64 v120, v[118:119], v[28:29] offset1:32
	v_mfma_f32_16x16x32_bf16 v[98:101], v[210:213], v[214:217], v[98:101]
	v_cvt_pk_bf16_f32 v28, v82, v83
	v_cvt_pk_bf16_f32 v29, v84, v85
	v_lshl_or_b32 v112, v112, 4, v152
	v_mfma_f32_16x16x32_bf16 v[70:73], v[206:209], v[222:225], v[70:73]
	v_cvt_pk_bf16_f32 v106, v106, v107
	v_cvt_pk_bf16_f32 v107, v108, v109
	v_bitop3_b32 v108, v126, v117, 2 bitop3:0x36
	v_mfma_f32_16x16x32_bf16 v[66:69], v[210:213], v[222:225], v[66:69]
	ds_write2st64_b64 v116, v[114:115], v[28:29] offset1:32
	v_cvt_pk_bf16_f32 v28, v78, v79
	v_cvt_pk_bf16_f32 v29, v80, v81
	v_lshl_add_u32 v108, v108, 4, v152
	v_cvt_pk_bf16_f32 v102, v102, v103
	v_cvt_pk_bf16_f32 v103, v104, v105
	v_bitop3_b32 v104, v126, v117, 4 bitop3:0x36
	ds_write2st64_b64 v112, v[110:111], v[28:29] offset0:16 offset1:48
	v_cvt_pk_bf16_f32 v28, v74, v75
	v_cvt_pk_bf16_f32 v29, v76, v77
	v_lshl_add_u32 v104, v104, 4, v152
	v_cvt_pk_bf16_f32 v98, v98, v99
	v_cvt_pk_bf16_f32 v99, v100, v101
	v_bitop3_b32 v100, v126, v117, 6 bitop3:0x36
	ds_write2st64_b64 v108, v[106:107], v[28:29] offset0:16 offset1:48
	v_cvt_pk_bf16_f32 v28, v70, v71
	v_cvt_pk_bf16_f32 v29, v72, v73
	v_mfma_f32_16x16x32_bf16 v[34:37], v[206:209], v[226:229], v[34:37]
	v_lshl_add_u32 v100, v100, 4, v152
	ds_write2st64_b64 v104, v[102:103], v[28:29] offset0:16 offset1:48
	v_cvt_pk_bf16_f32 v28, v66, v67
	v_mfma_f32_16x16x32_bf16 v[2:5], v[206:209], v[234:237], v[2:5]
	v_cvt_pk_bf16_f32 v29, v68, v69
	ds_write2st64_b64 v100, v[98:99], v[28:29] offset0:16 offset1:48
	s_nop 1
	v_cvt_pk_bf16_f32 v34, v34, v35
	v_mfma_f32_16x16x32_bf16 v[38:41], v[186:189], v[190:193], v[38:41]
	v_cvt_pk_bf16_f32 v35, v36, v37
	s_nop 0
	v_cvt_pk_bf16_f32 v2, v2, v3
	v_cvt_pk_bf16_f32 v3, v4, v5
	v_mfma_f32_16x16x32_bf16 v[6:9], v[178:181], v[190:193], v[6:9]
	ds_write2st64_b64 v104, v[34:35], v[2:3] offset0:80 offset1:112
	v_mfma_f32_16x16x32_bf16 v[28:31], v[210:213], v[226:229], v[30:33]
	v_mfma_f32_16x16x32_bf16 v[2:5], v[210:213], v[234:237], v[38:41]
	v_mfma_f32_16x16x32_bf16 v[62:65], v[198:201], v[144:147], v[62:65]
	s_nop 5
	v_cvt_pk_bf16_f32 v32, v28, v29
	v_cvt_pk_bf16_f32 v33, v30, v31
	v_cvt_pk_bf16_f32 v2, v2, v3
	v_mfma_f32_16x16x32_bf16 v[58:61], v[202:205], v[144:147], v[58:61]
	v_cvt_pk_bf16_f32 v3, v4, v5
	v_cvt_pk_bf16_f32 v62, v62, v63
	v_cvt_pk_bf16_f32 v63, v64, v65
	v_mfma_f32_16x16x32_bf16 v[54:57], v[206:209], v[144:147], v[54:57]
	ds_write2st64_b64 v100, v[32:33], v[2:3] offset0:80 offset1:112
	s_nop 2
	v_cvt_pk_bf16_f32 v58, v58, v59
	v_cvt_pk_bf16_f32 v59, v60, v61
	v_mfma_f32_16x16x32_bf16 v[50:53], v[210:213], v[144:147], v[50:53]
	v_and_b32_e32 v2, 0x1f0, v142
	v_cvt_pk_bf16_f32 v54, v54, v55
	v_cvt_pk_bf16_f32 v55, v56, v57
	v_mfma_f32_16x16x32_bf16 v[46:49], v[198:201], v[226:229], v[46:49]
	v_mfma_f32_16x16x32_bf16 v[42:45], v[202:205], v[226:229], v[42:45]
	s_nop 2
	v_cvt_pk_bf16_f32 v50, v50, v51
	v_cvt_pk_bf16_f32 v51, v52, v53
	s_nop 1
	v_cvt_pk_bf16_f32 v46, v46, v47
	v_mfma_f32_16x16x32_bf16 v[28:31], v[198:201], v[230:233], v[194:197]
	v_cvt_pk_bf16_f32 v47, v48, v49
	v_cvt_pk_bf16_f32 v42, v42, v43
	v_cvt_pk_bf16_f32 v43, v44, v45
	v_mfma_f32_16x16x32_bf16 v[22:25], v[202:205], v[230:233], v[22:25]
	v_mfma_f32_16x16x32_bf16 v[18:21], v[206:209], v[230:233], v[18:21]
	s_nop 2
	v_cvt_pk_bf16_f32 v28, v28, v29
	v_cvt_pk_bf16_f32 v29, v30, v31
	s_nop 1
	v_cvt_pk_bf16_f32 v22, v22, v23
	v_mfma_f32_16x16x32_bf16 v[14:17], v[210:213], v[230:233], v[14:17]
	v_cvt_pk_bf16_f32 v23, v24, v25
	v_cvt_pk_bf16_f32 v18, v18, v19
	v_cvt_pk_bf16_f32 v19, v20, v21
	v_mfma_f32_16x16x32_bf16 v[10:13], v[198:201], v[234:237], v[10:13]
	ds_write2st64_b64 v127, v[62:63], v[28:29] offset0:64 offset1:96
	s_nop 2
	v_cvt_pk_bf16_f32 v14, v14, v15
	v_cvt_pk_bf16_f32 v15, v16, v17
	v_mfma_f32_16x16x32_bf16 v[6:9], v[202:205], v[234:237], v[6:9]
	ds_write2st64_b64 v124, v[58:59], v[22:23] offset0:64 offset1:96
	v_cvt_pk_bf16_f32 v10, v10, v11
	v_cvt_pk_bf16_f32 v11, v12, v13
	ds_write2st64_b64 v120, v[54:55], v[18:19] offset0:64 offset1:96
	ds_write2st64_b64 v116, v[50:51], v[14:15] offset0:64 offset1:96
	s_nop 2
	v_cvt_pk_bf16_f32 v6, v6, v7
	v_cvt_pk_bf16_f32 v7, v8, v9
	ds_write2st64_b64 v112, v[46:47], v[10:11] offset0:80 offset1:112
	ds_write2st64_b64 v108, v[42:43], v[6:7] offset0:80 offset1:112
	s_waitcnt lgkmcnt(0)
	s_barrier

; #define GLDS_STAGE(st, kt_) do { \
;         _Pragma("unroll") for (int i_ = 0; i_ < FI; ++i_) { \
;             glds16(ap + (size_t)(32 * i_) * lda + (kt_) * 64, l3a + (st) + tid * 16 + i_ * 4096); \
;             glds16(bp + (size_t)(32 * i_) * ldb + (kt_) * 64, l3a + (st) + OPB + tid * 16 + i_ * 4096); } } while (0)
; #define GLDS_STAGE(st, kt_) do { \
;         _Pragma("unroll") for (int i_ = 0; i_ < 4; ++i_) { \
;             glds16(ap + (size_t)(64 * i_) * lda + (kt_) * 64, l3a + (st) + tid * 16 + i_ * 8192); \
;             glds16(bp + (size_t)(64 * i_) * ldb + (kt_) * 64, l3a + (st) + 32768 + tid * 16 + i_ * 8192); } } while (0)
; template <class Epi>
; DEV void gemm256_tile(const bf16_t* __restrict__ A, int lda, const bf16_t* __restrict__ Bt, int ldb, int K, unsigned char* lds, const Epi& epi) {
;     ...
;     GLDS_STAGE(0, 0);
;     const int aoff = (wr * 128 + fr) * 128, boff = 32768 + (wc * 64 + fr) * 128, sw = fr & 7;
;     for (int kt = 0; kt < nk; ++kt) {
;         const int cur = (kt & 1) * 65536;
;         asm volatile("s_waitcnt vmcnt(0)" ::: "memory");
;         __syncthreads();
;         if (kt + 1 < nk) GLDS_STAGE(cur ^ 65536, kt + 1);
; #pragma unroll
;         for (int kh = 0; kh < 2; ++kh) {
;             bf16x8 bfr[4];
;             const int ch = ((kh * 4 + fq) ^ sw) << 4;
; #pragma unroll
;             for (int i = 0; i < 4; ++i) bfr[i] = *(const bf16x8*)(lds + cur + boff + i * 2048 + ch);
; #pragma unroll
;             for (int mh = 0; mh < 2; ++mh) {
;                 bf16x8 af[4];
; #pragma unroll
;                 for (int i = 0; i < 4; ++i) af[i] = *(const bf16x8*)(lds + cur + aoff + (mh * 4 + i) * 2048 + ch);
; #pragma unroll
;                 for (int mi = 0; mi < 4; ++mi)
; #pragma unroll
;                     for (int ni = 0; ni < 4; ++ni) acc[mh * 4 + mi][ni] = __builtin_amdgcn_mfma_f32_16x16x32_bf16(bfr[ni], af[mi], acc[mh * 4 + mi][ni], 0, 0, 0);
.LBB0_1003:
	s_and_b32 s48, s25, 0x10000
	s_xor_b32 s49, s48, 0x10000
	v_add_u32_e32 v216, s49, v136
	v_add_u32_e32 v217, s49, v150
	s_waitcnt vmcnt(0) lgkmcnt(0)
	s_barrier
	v_or_b32_e32 v248, s48, v151
	v_add_u32_e32 v249, s48, v148
	v_add_u32_e32 v244, v248, v149
	v_add_u32_e32 v245, v249, v149
	ds_read_b128 v[152:155], v244 offset:32768
	ds_read_b128 v[176:179], v244 offset:34816
	ds_read_b128 v[180:183], v244 offset:36864
	ds_read_b128 v[184:187], v244 offset:38912
	ds_read_b128 v[228:231], v245
	ds_read_b128 v[232:235], v245 offset:2048
	ds_read_b128 v[236:239], v245 offset:4096
	ds_read_b128 v[240:243], v245 offset:6144
	v_readfirstlane_b32 s40, v216
	v_readfirstlane_b32 s44, v217
	v_add_u32_e32 v246, v248, v147
	v_add_u32_e32 v247, v249, v147
	s_mov_b32 m0, s40
	v_lshl_add_u64 v[204:205], v[138:139], 0, s[6:7]
	global_load_lds_dwordx4 v[138:139], off
	s_mov_b32 m0, s44
	v_lshl_add_u64 v[210:211], v[140:141], 0, s[6:7]
	global_load_lds_dwordx4 v[140:141], off
	s_add_i32 s41, s40, 0x2000
	s_add_i32 s45, s44, 0x2000
	s_add_i32 s42, s40, 0x4000
	s_add_i32 s46, s44, 0x4000
	s_add_i32 s43, s40, 0x6000
	s_add_i32 s47, s44, 0x6000
	s_add_i32 s25, s25, 0x10000
	v_lshl_add_u64 v[206:207], v[138:139], 0, s[8:9]
	v_lshl_add_u64 v[212:213], v[140:141], 0, s[8:9]
	v_lshl_add_u64 v[208:209], v[138:139], 0, s[10:11]
	v_lshl_add_u64 v[214:215], v[140:141], 0, s[10:11]
	s_waitcnt lgkmcnt(3)
	v_mfma_f32_16x16x32_bf16 v[126:129], v[152:155], v[228:231], v[126:129]
	s_mov_b32 m0, s41
	v_mfma_f32_16x16x32_bf16 v[122:125], v[176:179], v[228:231], v[122:125]
	global_load_lds_dwordx4 v[204:205], off
	v_mfma_f32_16x16x32_bf16 v[118:121], v[180:183], v[228:231], v[118:121]
	s_mov_b32 m0, s45
	v_mfma_f32_16x16x32_bf16 v[114:117], v[184:187], v[228:231], v[114:117]
	global_load_lds_dwordx4 v[210:211], off
	s_waitcnt lgkmcnt(2)
	v_mfma_f32_16x16x32_bf16 v[110:113], v[152:155], v[232:235], v[110:113]
	v_mfma_f32_16x16x32_bf16 v[106:109], v[176:179], v[232:235], v[106:109]
	v_mfma_f32_16x16x32_bf16 v[102:105], v[180:183], v[232:235], v[102:105]
	v_mfma_f32_16x16x32_bf16 v[98:101], v[184:187], v[232:235], v[98:101]
	s_waitcnt lgkmcnt(1)
	v_mfma_f32_16x16x32_bf16 v[94:97], v[152:155], v[236:239], v[94:97]
	ds_read_b128 v[228:231], v245 offset:8192
	v_mfma_f32_16x16x32_bf16 v[90:93], v[176:179], v[236:239], v[90:93]
	ds_read_b128 v[232:235], v245 offset:10240
	v_mfma_f32_16x16x32_bf16 v[86:89], v[180:183], v[236:239], v[86:89]
	s_mov_b32 m0, s42
	v_mfma_f32_16x16x32_bf16 v[82:85], v[184:187], v[236:239], v[82:85]
	global_load_lds_dwordx4 v[206:207], off
	s_waitcnt lgkmcnt(2)
	v_mfma_f32_16x16x32_bf16 v[78:81], v[152:155], v[240:243], v[78:81]
	s_mov_b32 m0, s46
	v_mfma_f32_16x16x32_bf16 v[74:77], v[176:179], v[240:243], v[74:77]
	global_load_lds_dwordx4 v[212:213], off
	v_mfma_f32_16x16x32_bf16 v[70:73], v[180:183], v[240:243], v[70:73]
	v_mfma_f32_16x16x32_bf16 v[66:69], v[184:187], v[240:243], v[66:69]
	s_waitcnt lgkmcnt(1)
	v_mfma_f32_16x16x32_bf16 v[62:65], v[152:155], v[228:231], v[62:65]
	ds_read_b128 v[236:239], v245 offset:12288
	v_mfma_f32_16x16x32_bf16 v[58:61], v[176:179], v[228:231], v[58:61]
	ds_read_b128 v[240:243], v245 offset:14336
	v_mfma_f32_16x16x32_bf16 v[54:57], v[180:183], v[228:231], v[54:57]
	s_mov_b32 m0, s43
	v_mfma_f32_16x16x32_bf16 v[50:53], v[184:187], v[228:231], v[50:53]
	global_load_lds_dwordx4 v[208:209], off
	s_waitcnt lgkmcnt(2)
	v_mfma_f32_16x16x32_bf16 v[46:49], v[152:155], v[232:235], v[46:49]
	s_mov_b32 m0, s47
	v_mfma_f32_16x16x32_bf16 v[42:45], v[176:179], v[232:235], v[42:45]
	global_load_lds_dwordx4 v[214:215], off
	v_mfma_f32_16x16x32_bf16 v[34:37], v[180:183], v[232:235], v[34:37]
	v_lshl_add_u64 v[138:139], v[138:139], 0, s[12:13]
	v_mfma_f32_16x16x32_bf16 v[30:33], v[184:187], v[232:235], v[30:33]
	v_lshl_add_u64 v[140:141], v[140:141], 0, s[12:13]
	s_waitcnt lgkmcnt(1)
	v_mfma_f32_16x16x32_bf16 v[26:29], v[152:155], v[236:239], v[26:29]
	ds_read_b128 v[188:191], v246 offset:32768
	v_mfma_f32_16x16x32_bf16 v[22:25], v[176:179], v[236:239], v[22:25]
	ds_read_b128 v[192:195], v246 offset:34816
	v_mfma_f32_16x16x32_bf16 v[18:21], v[180:183], v[236:239], v[18:21]
	ds_read_b128 v[220:223], v246 offset:36864
	v_mfma_f32_16x16x32_bf16 v[14:17], v[184:187], v[236:239], v[14:17]
	ds_read_b128 v[224:227], v246 offset:38912
	s_waitcnt lgkmcnt(4)
	v_mfma_f32_16x16x32_bf16 v[10:13], v[152:155], v[240:243], v[10:13]
	ds_read_b128 v[228:231], v247
	v_mfma_f32_16x16x32_bf16 v[6:9], v[176:179], v[240:243], v[6:9]
	ds_read_b128 v[232:235], v247 offset:2048
	v_mfma_f32_16x16x32_bf16 v[2:5], v[180:183], v[240:243], v[2:5]
	v_mfma_f32_16x16x32_bf16 v[38:41], v[184:187], v[240:243], v[38:41]
	s_waitcnt lgkmcnt(1)
	v_mfma_f32_16x16x32_bf16 v[126:129], v[188:191], v[228:231], v[126:129]
	ds_read_b128 v[236:239], v247 offset:4096
	v_mfma_f32_16x16x32_bf16 v[122:125], v[192:195], v[228:231], v[122:125]
	ds_read_b128 v[240:243], v247 offset:6144
	v_mfma_f32_16x16x32_bf16 v[118:121], v[220:223], v[228:231], v[118:121]
	v_mfma_f32_16x16x32_bf16 v[114:117], v[224:227], v[228:231], v[114:117]
	s_waitcnt lgkmcnt(2)
	v_mfma_f32_16x16x32_bf16 v[110:113], v[188:191], v[232:235], v[110:113]
	v_mfma_f32_16x16x32_bf16 v[106:109], v[192:195], v[232:235], v[106:109]
	v_mfma_f32_16x16x32_bf16 v[102:105], v[220:223], v[232:235], v[102:105]
	v_mfma_f32_16x16x32_bf16 v[98:101], v[224:227], v[232:235], v[98:101]
	s_waitcnt lgkmcnt(1)
	v_mfma_f32_16x16x32_bf16 v[94:97], v[188:191], v[236:239], v[94:97]
	ds_read_b128 v[228:231], v247 offset:8192
	v_mfma_f32_16x16x32_bf16 v[90:93], v[192:195], v[236:239], v[90:93]
	ds_read_b128 v[232:235], v247 offset:10240
	v_mfma_f32_16x16x32_bf16 v[86:89], v[220:223], v[236:239], v[86:89]
	v_mfma_f32_16x16x32_bf16 v[82:85], v[224:227], v[236:239], v[82:85]
	s_waitcnt lgkmcnt(2)
; DEV unsigned cvt_pk_bf16(float lo, float hi) { const f32x2_t v = {lo, hi}; const bf16x2_t b = __builtin_convertvector(v, bf16x2_t); return __builtin_bit_cast(unsigned, b); }
; #define GLDS_STAGE(st, kt_) do { \
;         _Pragma("unroll") for (int i_ = 0; i_ < FI; ++i_) { \
;             glds16(ap + (size_t)(32 * i_) * lda + (kt_) * 64, l3a + (st) + tid * 16 + i_ * 4096); \
;             glds16(bp + (size_t)(32 * i_) * ldb + (kt_) * 64, l3a + (st) + OPB + tid * 16 + i_ * 4096); } } while (0)
; template <class Epi>
; DEV void gemm256_tile(const bf16_t* __restrict__ A, int lda, const bf16_t* __restrict__ Bt, int ldb, int K, unsigned char* lds, const Epi& epi) {
;     ...
;     for (int kt = 0; kt < nk; ++kt) {
;         const int cur = (kt & 1) * 65536;
;         asm volatile("s_waitcnt vmcnt(0)" ::: "memory");
;         __syncthreads();
;         if (kt + 1 < nk) GLDS_STAGE(cur ^ 65536, kt + 1);
; #pragma unroll
;         for (int kh = 0; kh < 2; ++kh) {
;             bf16x8 bfr[4];
;             const int ch = ((kh * 4 + fq) ^ sw) << 4;
; #pragma unroll
;             for (int i = 0; i < 4; ++i) bfr[i] = *(const bf16x8*)(lds + cur + boff + i * 2048 + ch);
; #pragma unroll
;             for (int mh = 0; mh < 2; ++mh) {
;                 bf16x8 af[4];
; #pragma unroll
;                 for (int i = 0; i < 4; ++i) af[i] = *(const bf16x8*)(lds + cur + aoff + (mh * 4 + i) * 2048 + ch);
; #pragma unroll
;                 for (int mi = 0; mi < 4; ++mi)
; #pragma unroll
;                     for (int ni = 0; ni < 4; ++ni) acc[mh * 4 + mi][ni] = __builtin_amdgcn_mfma_f32_16x16x32_bf16(bfr[ni], af[mi], acc[mh * 4 + mi][ni], 0, 0, 0);
;             }
;         }
;     }
;     ...
;     __syncthreads();
;     if constexpr (Epi::STAGE) {
; #pragma unroll
;         for (int mi = 0; mi < 8; ++mi)
; #pragma unroll
;             for (int ni = 0; ni < 4; ++ni) {
;                 const int row = wr * 128 + mi * 16 + fr, col = wc * 64 + ni * 16 + fq * 4;
;                 const f32x4 v = epi.xform(row, col, acc[mi][ni]);
;                 uint2 w; w.x = cvt_pk_bf16(v[0], v[1]); w.y = cvt_pk_bf16(v[2], v[3]);
;                 *(uint2*)(lds + row * 512 + ((((col >> 3) ^ (row & 31)) << 4) | (((col >> 2) & 1) << 3))) = w;
	v_mfma_f32_16x16x32_bf16 v[78:81], v[188:191], v[240:243], v[78:81]
	v_mfma_f32_16x16x32_bf16 v[74:77], v[192:195], v[240:243], v[74:77]
	v_mfma_f32_16x16x32_bf16 v[70:73], v[220:223], v[240:243], v[70:73]
	v_mfma_f32_16x16x32_bf16 v[66:69], v[224:227], v[240:243], v[66:69]
	s_waitcnt lgkmcnt(1)
	v_mfma_f32_16x16x32_bf16 v[62:65], v[188:191], v[228:231], v[62:65]
	ds_read_b128 v[236:239], v247 offset:12288
	v_mfma_f32_16x16x32_bf16 v[58:61], v[192:195], v[228:231], v[58:61]
	ds_read_b128 v[240:243], v247 offset:14336
	v_mfma_f32_16x16x32_bf16 v[54:57], v[220:223], v[228:231], v[54:57]
	v_mfma_f32_16x16x32_bf16 v[50:53], v[224:227], v[228:231], v[50:53]
	s_waitcnt lgkmcnt(2)
	v_mfma_f32_16x16x32_bf16 v[46:49], v[188:191], v[232:235], v[46:49]
	v_mfma_f32_16x16x32_bf16 v[42:45], v[192:195], v[232:235], v[42:45]
	v_mfma_f32_16x16x32_bf16 v[34:37], v[220:223], v[232:235], v[34:37]
	v_mfma_f32_16x16x32_bf16 v[30:33], v[224:227], v[232:235], v[30:33]
	s_waitcnt lgkmcnt(1)
	v_mfma_f32_16x16x32_bf16 v[26:29], v[188:191], v[236:239], v[26:29]
	v_mfma_f32_16x16x32_bf16 v[22:25], v[192:195], v[236:239], v[22:25]
	v_mfma_f32_16x16x32_bf16 v[18:21], v[220:223], v[236:239], v[18:21]
	v_mfma_f32_16x16x32_bf16 v[14:17], v[224:227], v[236:239], v[14:17]
	s_waitcnt lgkmcnt(0)
	v_mfma_f32_16x16x32_bf16 v[10:13], v[188:191], v[240:243], v[10:13]
	v_mfma_f32_16x16x32_bf16 v[6:9], v[192:195], v[240:243], v[6:9]
	v_mfma_f32_16x16x32_bf16 v[2:5], v[220:223], v[240:243], v[2:5]
	v_mfma_f32_16x16x32_bf16 v[38:41], v[224:227], v[240:243], v[38:41]
	s_cmp_eq_u32 s25, 0x1f0000
	s_cbranch_scc0 .LBB0_1003
	v_or_b32_e32 v172, 0x18000, v151
	v_add_u32_e32 v156, v172, v149
	s_waitcnt vmcnt(0)
	s_barrier
	ds_read_b128 v[138:141], v156
	ds_read_b128 v[152:155], v156 offset:2048
	ds_read_b128 v[176:179], v156 offset:4096
	ds_read_b128 v[180:183], v156 offset:6144
	v_add_u32_e32 v173, 0x10000, v148
	v_add_u32_e32 v188, v173, v149
	ds_read_b128 v[148:151], v188
	s_waitcnt lgkmcnt(0)
	v_mfma_f32_16x16x32_bf16 v[126:129], v[138:141], v[148:151], v[126:129]
	s_sext_i32_i8 s14, s24
	s_lshl_b32 s24, s14, 8
	s_lshl_b64 s[16:17], s[16:17], 21
	v_mfma_f32_16x16x32_bf16 v[122:125], v[152:155], v[148:151], v[122:125]
	s_ashr_i32 s25, s24, 31
	s_add_u32 s14, s4, s16
	s_addc_u32 s15, s5, s17
	v_mfma_f32_16x16x32_bf16 v[118:121], v[176:179], v[148:151], v[118:121]
	s_lshl_b64 s[16:17], s[24:25], 2
	v_lshl_add_u64 v[156:157], v[130:131], 0, s[18:19]
	s_add_u32 s16, s14, s16
	v_mfma_f32_16x16x32_bf16 v[114:117], v[180:183], v[148:151], v[114:117]
	ds_read_b128 v[148:151], v188 offset:2048
	s_addc_u32 s17, s15, s17
	s_mov_b32 s18, 0
	s_waitcnt lgkmcnt(0)
	v_mfma_f32_16x16x32_bf16 v[110:113], v[138:141], v[148:151], v[110:113]
	v_mfma_f32_16x16x32_bf16 v[106:109], v[152:155], v[148:151], v[106:109]
	v_mfma_f32_16x16x32_bf16 v[102:105], v[176:179], v[148:151], v[102:105]
	v_mfma_f32_16x16x32_bf16 v[98:101], v[180:183], v[148:151], v[98:101]
	ds_read_b128 v[148:151], v188 offset:4096
	s_waitcnt lgkmcnt(0)
	v_mfma_f32_16x16x32_bf16 v[94:97], v[138:141], v[148:151], v[94:97]
	v_mfma_f32_16x16x32_bf16 v[90:93], v[152:155], v[148:151], v[90:93]
	v_mfma_f32_16x16x32_bf16 v[86:89], v[176:179], v[148:151], v[86:89]
	v_mfma_f32_16x16x32_bf16 v[82:85], v[180:183], v[148:151], v[82:85]
	ds_read_b128 v[148:151], v188 offset:6144
	s_waitcnt lgkmcnt(0)
	v_mfma_f32_16x16x32_bf16 v[78:81], v[138:141], v[148:151], v[78:81]
	v_mfma_f32_16x16x32_bf16 v[74:77], v[152:155], v[148:151], v[74:77]
	v_mfma_f32_16x16x32_bf16 v[70:73], v[176:179], v[148:151], v[70:73]
	v_mfma_f32_16x16x32_bf16 v[66:69], v[180:183], v[148:151], v[66:69]
	ds_read_b128 v[148:151], v188 offset:8192
	ds_read_b128 v[184:187], v188 offset:10240
	s_waitcnt lgkmcnt(1)
	v_mfma_f32_16x16x32_bf16 v[62:65], v[138:141], v[148:151], v[62:65]
	v_mfma_f32_16x16x32_bf16 v[58:61], v[152:155], v[148:151], v[58:61]
	v_mfma_f32_16x16x32_bf16 v[54:57], v[176:179], v[148:151], v[54:57]
	v_mfma_f32_16x16x32_bf16 v[50:53], v[180:183], v[148:151], v[50:53]
	ds_read_b128 v[148:151], v188 offset:12288
	s_waitcnt lgkmcnt(1)
	v_mfma_f32_16x16x32_bf16 v[46:49], v[138:141], v[184:187], v[46:49]
	v_mfma_f32_16x16x32_bf16 v[42:45], v[152:155], v[184:187], v[42:45]
	v_mfma_f32_16x16x32_bf16 v[34:37], v[176:179], v[184:187], v[34:37]
	v_mfma_f32_16x16x32_bf16 v[30:33], v[180:183], v[184:187], v[30:33]
	ds_read_b128 v[184:187], v188 offset:14336
	s_waitcnt lgkmcnt(1)
	v_mfma_f32_16x16x32_bf16 v[188:191], v[138:141], v[148:151], v[26:29]
	s_nop 2
	v_add_u32_e32 v29, v172, v147
	ds_read_b128 v[192:195], v29
	ds_read_b128 v[196:199], v29 offset:2048
	ds_read_b128 v[200:203], v29 offset:4096
	ds_read_b128 v[204:207], v29 offset:6144
	v_add_u32_e32 v29, v173, v147
	v_mfma_f32_16x16x32_bf16 v[22:25], v[152:155], v[148:151], v[22:25]
	v_and_b32_e32 v28, 0xc0, v142
	v_lshl_or_b32 v145, v145, 2, v28
	v_lshlrev_b32_e32 v28, 3, v144
	v_mfma_f32_16x16x32_bf16 v[18:21], v[176:179], v[148:151], v[18:21]
	v_lshl_add_u64 v[26:27], s[24:25], 1, v[156:157]
	v_mfma_f32_16x16x32_bf16 v[14:17], v[180:183], v[148:151], v[14:17]
	ds_read_b128 v[148:151], v29
	ds_read_b128 v[208:211], v29 offset:2048
	ds_read_b128 v[212:215], v29 offset:4096
	ds_read_b128 v[216:219], v29 offset:6144
	s_waitcnt lgkmcnt(3)
	v_mfma_f32_16x16x32_bf16 v[126:129], v[192:195], v[148:151], v[126:129]
	v_mfma_f32_16x16x32_bf16 v[122:125], v[196:199], v[148:151], v[122:125]
	s_waitcnt lgkmcnt(1)
	v_mfma_f32_16x16x32_bf16 v[94:97], v[192:195], v[212:215], v[94:97]
	v_mfma_f32_16x16x32_bf16 v[10:13], v[138:141], v[184:187], v[10:13]
	ds_read_b128 v[138:141], v29 offset:8192
	ds_read_b128 v[220:223], v29 offset:10240
	ds_read_b128 v[224:227], v29 offset:12288
	ds_read_b128 v[228:231], v29 offset:14336
	v_lshlrev_b32_e32 v29, 9, v146
	v_and_or_b32 v144, v28, 8, v29
	v_mfma_f32_16x16x32_bf16 v[118:121], v[200:203], v[148:151], v[118:121]
	v_cvt_pk_bf16_f32 v28, v126, v127
	v_lshrrev_b32_e32 v126, 3, v145
	v_xor_b32_e32 v127, v126, v143
	v_mfma_f32_16x16x32_bf16 v[90:93], v[196:199], v[212:215], v[90:93]
	v_cvt_pk_bf16_f32 v29, v128, v129
	v_lshl_or_b32 v127, v127, 4, v144
	v_cvt_pk_bf16_f32 v122, v122, v123
	v_mfma_f32_16x16x32_bf16 v[114:117], v[204:207], v[148:151], v[114:117]
	v_cvt_pk_bf16_f32 v123, v124, v125
	v_bitop3_b32 v124, v126, v143, 2 bitop3:0x36
	v_cvt_pk_bf16_f32 v94, v94, v95
	v_mfma_f32_16x16x32_bf16 v[86:89], v[200:203], v[212:215], v[86:89]
	v_cvt_pk_bf16_f32 v95, v96, v97
	s_waitcnt lgkmcnt(0)
	s_barrier
; DEV unsigned cvt_pk_bf16(float lo, float hi) { const f32x2_t v = {lo, hi}; const bf16x2_t b = __builtin_convertvector(v, bf16x2_t); return __builtin_bit_cast(unsigned, b); }
; template <class Epi>
; DEV void gemm256_tile(const bf16_t* __restrict__ A, int lda, const bf16_t* __restrict__ Bt, int ldb, int K, unsigned char* lds, const Epi& epi) {
;     ...
;                 for (int mi = 0; mi < 4; ++mi)
; #pragma unroll
;                     for (int ni = 0; ni < 4; ++ni) acc[mh * 4 + mi][ni] = __builtin_amdgcn_mfma_f32_16x16x32_bf16(bfr[ni], af[mi], acc[mh * 4 + mi][ni], 0, 0, 0);
;             }
;         }
;     }
;     ...
;     __syncthreads();
;     if constexpr (Epi::STAGE) {
; #pragma unroll
;         for (int mi = 0; mi < 8; ++mi)
; #pragma unroll
;             for (int ni = 0; ni < 4; ++ni) {
;                 const int row = wr * 128 + mi * 16 + fr, col = wc * 64 + ni * 16 + fq * 4;
;                 const f32x4 v = epi.xform(row, col, acc[mi][ni]);
;                 uint2 w; w.x = cvt_pk_bf16(v[0], v[1]); w.y = cvt_pk_bf16(v[2], v[3]);
;                 *(uint2*)(lds + row * 512 + ((((col >> 3) ^ (row & 31)) << 4) | (((col >> 2) & 1) << 3))) = w;
;             }
;         __syncthreads();
	v_mfma_f32_16x16x32_bf16 v[110:113], v[192:195], v[208:211], v[110:113]
	v_lshl_add_u32 v124, v124, 4, v144
	v_cvt_pk_bf16_f32 v118, v118, v119
	v_mfma_f32_16x16x32_bf16 v[82:85], v[204:207], v[212:215], v[82:85]
	v_cvt_pk_bf16_f32 v119, v120, v121
	v_bitop3_b32 v120, v126, v143, 4 bitop3:0x36
	ds_write2st64_b64 v127, v[28:29], v[94:95] offset1:32
	v_mfma_f32_16x16x32_bf16 v[106:109], v[196:199], v[208:211], v[106:109]
	v_cvt_pk_bf16_f32 v28, v90, v91
	v_cvt_pk_bf16_f32 v29, v92, v93
	v_lshl_add_u32 v120, v120, 4, v144
	v_mfma_f32_16x16x32_bf16 v[78:81], v[192:195], v[216:219], v[78:81]
	v_cvt_pk_bf16_f32 v114, v114, v115
	v_cvt_pk_bf16_f32 v115, v116, v117
	v_bitop3_b32 v116, v126, v143, 6 bitop3:0x36
	v_mfma_f32_16x16x32_bf16 v[102:105], v[200:203], v[208:211], v[102:105]
	ds_write2st64_b64 v124, v[122:123], v[28:29] offset1:32
	v_cvt_pk_bf16_f32 v28, v86, v87
	v_cvt_pk_bf16_f32 v29, v88, v89
	v_mfma_f32_16x16x32_bf16 v[74:77], v[196:199], v[216:219], v[74:77]
	v_lshl_add_u32 v116, v116, 4, v144
	v_or_b32_e32 v117, 16, v143
	v_cvt_pk_bf16_f32 v110, v110, v111
	v_mfma_f32_16x16x32_bf16 v[2:5], v[176:179], v[184:187], v[2:5]
	v_cvt_pk_bf16_f32 v111, v112, v113
	v_bitop3_b32 v112, v126, v143, 16 bitop3:0x1e
	ds_write2st64_b64 v120, v[118:119], v[28:29] offset1:32
	v_mfma_f32_16x16x32_bf16 v[98:101], v[204:207], v[208:211], v[98:101]
	v_cvt_pk_bf16_f32 v28, v82, v83
	v_cvt_pk_bf16_f32 v29, v84, v85
	v_lshl_or_b32 v112, v112, 4, v144
	v_mfma_f32_16x16x32_bf16 v[70:73], v[200:203], v[216:219], v[70:73]
	v_cvt_pk_bf16_f32 v106, v106, v107
	v_cvt_pk_bf16_f32 v107, v108, v109
	v_bitop3_b32 v108, v126, v117, 2 bitop3:0x36
	v_mfma_f32_16x16x32_bf16 v[66:69], v[204:207], v[216:219], v[66:69]
	ds_write2st64_b64 v116, v[114:115], v[28:29] offset1:32
	v_cvt_pk_bf16_f32 v28, v78, v79
	v_cvt_pk_bf16_f32 v29, v80, v81
	v_lshl_add_u32 v108, v108, 4, v144
	v_cvt_pk_bf16_f32 v102, v102, v103
	v_cvt_pk_bf16_f32 v103, v104, v105
	v_bitop3_b32 v104, v126, v117, 4 bitop3:0x36
	ds_write2st64_b64 v112, v[110:111], v[28:29] offset0:16 offset1:48
	v_cvt_pk_bf16_f32 v28, v74, v75
	v_cvt_pk_bf16_f32 v29, v76, v77
	v_lshl_add_u32 v104, v104, 4, v144
	v_cvt_pk_bf16_f32 v98, v98, v99
	v_cvt_pk_bf16_f32 v99, v100, v101
	v_bitop3_b32 v100, v126, v117, 6 bitop3:0x36
	ds_write2st64_b64 v108, v[106:107], v[28:29] offset0:16 offset1:48
	v_cvt_pk_bf16_f32 v28, v70, v71
	v_cvt_pk_bf16_f32 v29, v72, v73
	v_mfma_f32_16x16x32_bf16 v[34:37], v[200:203], v[220:223], v[34:37]
	v_lshl_add_u32 v100, v100, 4, v144
	ds_write2st64_b64 v104, v[102:103], v[28:29] offset0:16 offset1:48
	v_cvt_pk_bf16_f32 v28, v66, v67
	v_mfma_f32_16x16x32_bf16 v[2:5], v[200:203], v[228:231], v[2:5]
	v_cvt_pk_bf16_f32 v29, v68, v69
	ds_write2st64_b64 v100, v[98:99], v[28:29] offset0:16 offset1:48
	s_nop 1
	v_cvt_pk_bf16_f32 v34, v34, v35
	v_mfma_f32_16x16x32_bf16 v[38:41], v[180:183], v[184:187], v[38:41]
	v_cvt_pk_bf16_f32 v35, v36, v37
	s_nop 0
	v_cvt_pk_bf16_f32 v2, v2, v3
	v_cvt_pk_bf16_f32 v3, v4, v5
	v_mfma_f32_16x16x32_bf16 v[6:9], v[152:155], v[184:187], v[6:9]
	ds_write2st64_b64 v104, v[34:35], v[2:3] offset0:80 offset1:112
	v_mfma_f32_16x16x32_bf16 v[28:31], v[204:207], v[220:223], v[30:33]
	v_mfma_f32_16x16x32_bf16 v[2:5], v[204:207], v[228:231], v[38:41]
	v_mfma_f32_16x16x32_bf16 v[62:65], v[192:195], v[138:141], v[62:65]
	s_nop 5
	v_cvt_pk_bf16_f32 v32, v28, v29
	v_cvt_pk_bf16_f32 v33, v30, v31
	v_cvt_pk_bf16_f32 v2, v2, v3
	v_mfma_f32_16x16x32_bf16 v[58:61], v[196:199], v[138:141], v[58:61]
	v_cvt_pk_bf16_f32 v3, v4, v5
	v_cvt_pk_bf16_f32 v62, v62, v63
	v_cvt_pk_bf16_f32 v63, v64, v65
	v_mfma_f32_16x16x32_bf16 v[54:57], v[200:203], v[138:141], v[54:57]
	ds_write2st64_b64 v100, v[32:33], v[2:3] offset0:80 offset1:112
	s_nop 2
	v_cvt_pk_bf16_f32 v58, v58, v59
	v_cvt_pk_bf16_f32 v59, v60, v61
	v_mfma_f32_16x16x32_bf16 v[50:53], v[204:207], v[138:141], v[50:53]
	v_and_b32_e32 v2, 0x1f0, v136
	v_cvt_pk_bf16_f32 v54, v54, v55
	v_cvt_pk_bf16_f32 v55, v56, v57
	v_mfma_f32_16x16x32_bf16 v[46:49], v[192:195], v[220:223], v[46:49]
	v_mfma_f32_16x16x32_bf16 v[42:45], v[196:199], v[220:223], v[42:45]
	s_nop 2
	v_cvt_pk_bf16_f32 v50, v50, v51
	v_cvt_pk_bf16_f32 v51, v52, v53
	s_nop 1
	v_cvt_pk_bf16_f32 v46, v46, v47
	v_mfma_f32_16x16x32_bf16 v[28:31], v[192:195], v[224:227], v[188:191]
	v_cvt_pk_bf16_f32 v47, v48, v49
	v_cvt_pk_bf16_f32 v42, v42, v43
	v_cvt_pk_bf16_f32 v43, v44, v45
	v_mfma_f32_16x16x32_bf16 v[22:25], v[196:199], v[224:227], v[22:25]
	v_mfma_f32_16x16x32_bf16 v[18:21], v[200:203], v[224:227], v[18:21]
	s_nop 2
	v_cvt_pk_bf16_f32 v28, v28, v29
	v_cvt_pk_bf16_f32 v29, v30, v31
	s_nop 1
	v_cvt_pk_bf16_f32 v22, v22, v23
	v_mfma_f32_16x16x32_bf16 v[14:17], v[204:207], v[224:227], v[14:17]
	v_cvt_pk_bf16_f32 v23, v24, v25
	v_cvt_pk_bf16_f32 v18, v18, v19
	v_cvt_pk_bf16_f32 v19, v20, v21
	v_mfma_f32_16x16x32_bf16 v[10:13], v[192:195], v[228:231], v[10:13]
	ds_write2st64_b64 v127, v[62:63], v[28:29] offset0:64 offset1:96
	s_nop 2
	v_cvt_pk_bf16_f32 v14, v14, v15
	v_cvt_pk_bf16_f32 v15, v16, v17
	v_mfma_f32_16x16x32_bf16 v[6:9], v[196:199], v[228:231], v[6:9]
	ds_write2st64_b64 v124, v[58:59], v[22:23] offset0:64 offset1:96
	v_cvt_pk_bf16_f32 v10, v10, v11
	v_cvt_pk_bf16_f32 v11, v12, v13
	ds_write2st64_b64 v120, v[54:55], v[18:19] offset0:64 offset1:96
	ds_write2st64_b64 v116, v[50:51], v[14:15] offset0:64 offset1:96
	s_nop 2
	v_cvt_pk_bf16_f32 v6, v6, v7
	v_cvt_pk_bf16_f32 v7, v8, v9
	ds_write2st64_b64 v112, v[46:47], v[10:11] offset0:80 offset1:112
	ds_write2st64_b64 v108, v[42:43], v[6:7] offset0:80 offset1:112
	s_waitcnt lgkmcnt(0)
	s_barrier

; #define GLDS_STAGE(st, kt_) do { \
;         _Pragma("unroll") for (int i_ = 0; i_ < FI; ++i_) { \
;             glds16(ap + (size_t)(32 * i_) * lda + (kt_) * 64, l3a + (st) + tid * 16 + i_ * 4096); \
;             glds16(bp + (size_t)(32 * i_) * ldb + (kt_) * 64, l3a + (st) + OPB + tid * 16 + i_ * 4096); } } while (0)
; #define GLDS_STAGE(st, kt_) do { \
;         _Pragma("unroll") for (int i_ = 0; i_ < 4; ++i_) { \
;             glds16(ap + (size_t)(64 * i_) * lda + (kt_) * 64, l3a + (st) + tid * 16 + i_ * 8192); \
;             glds16(bp + (size_t)(64 * i_) * ldb + (kt_) * 64, l3a + (st) + 32768 + tid * 16 + i_ * 8192); } } while (0)
; template <class Epi>
; DEV void gemm256_tile(const bf16_t* __restrict__ A, int lda, const bf16_t* __restrict__ Bt, int ldb, int K, unsigned char* lds, const Epi& epi) {
;     ...
;     GLDS_STAGE(0, 0);
;     const int aoff = (wr * 128 + fr) * 128, boff = 32768 + (wc * 64 + fr) * 128, sw = fr & 7;
;     for (int kt = 0; kt < nk; ++kt) {
;         const int cur = (kt & 1) * 65536;
;         asm volatile("s_waitcnt vmcnt(0)" ::: "memory");
;         __syncthreads();
;         if (kt + 1 < nk) GLDS_STAGE(cur ^ 65536, kt + 1);
; #pragma unroll
;         for (int kh = 0; kh < 2; ++kh) {
;             bf16x8 bfr[4];
;             const int ch = ((kh * 4 + fq) ^ sw) << 4;
; #pragma unroll
;             for (int i = 0; i < 4; ++i) bfr[i] = *(const bf16x8*)(lds + cur + boff + i * 2048 + ch);
; #pragma unroll
;             for (int mh = 0; mh < 2; ++mh) {
;                 bf16x8 af[4];
; #pragma unroll
;                 for (int i = 0; i < 4; ++i) af[i] = *(const bf16x8*)(lds + cur + aoff + (mh * 4 + i) * 2048 + ch);
; #pragma unroll
;                 for (int mi = 0; mi < 4; ++mi)
; #pragma unroll
;                     for (int ni = 0; ni < 4; ++ni) acc[mh * 4 + mi][ni] = __builtin_amdgcn_mfma_f32_16x16x32_bf16(bfr[ni], af[mi], acc[mh * 4 + mi][ni], 0, 0, 0);
.LBB0_1236:
	s_and_b32 s48, s21, 0x10000
	s_xor_b32 s49, s48, 0x10000
	v_add_u32_e32 v216, s49, v138
	v_add_u32_e32 v217, s49, v150
	s_waitcnt vmcnt(0) lgkmcnt(0)
	s_barrier
	v_or_b32_e32 v248, s48, v153
	v_add_u32_e32 v249, s48, v151
	v_add_u32_e32 v244, v248, v152
	v_add_u32_e32 v245, v249, v152
	ds_read_b128 v[154:157], v244 offset:32768
	ds_read_b128 v[170:173], v244 offset:34816
	ds_read_b128 v[174:177], v244 offset:36864
	ds_read_b128 v[178:181], v244 offset:38912
	ds_read_b128 v[228:231], v245
	ds_read_b128 v[232:235], v245 offset:2048
	ds_read_b128 v[236:239], v245 offset:4096
	ds_read_b128 v[240:243], v245 offset:6144
	v_readfirstlane_b32 s40, v216
	v_readfirstlane_b32 s44, v217
	v_add_u32_e32 v246, v248, v149
	v_add_u32_e32 v247, v249, v149
	s_mov_b32 m0, s40
	v_lshl_add_u64 v[204:205], v[140:141], 0, s[4:5]
	global_load_lds_dwordx4 v[140:141], off
	s_mov_b32 m0, s44
	v_lshl_add_u64 v[210:211], v[142:143], 0, s[4:5]
	global_load_lds_dwordx4 v[142:143], off
	s_add_i32 s41, s40, 0x2000
	s_add_i32 s45, s44, 0x2000
	s_add_i32 s42, s40, 0x4000
	s_add_i32 s46, s44, 0x4000
	s_add_i32 s43, s40, 0x6000
	s_add_i32 s47, s44, 0x6000
	s_add_i32 s21, s21, 0x10000
	v_lshl_add_u64 v[206:207], v[140:141], 0, s[6:7]
	v_lshl_add_u64 v[212:213], v[142:143], 0, s[6:7]
	v_lshl_add_u64 v[208:209], v[140:141], 0, s[8:9]
	v_lshl_add_u64 v[214:215], v[142:143], 0, s[8:9]
	s_waitcnt lgkmcnt(3)
	v_mfma_f32_16x16x32_bf16 v[126:129], v[154:157], v[228:231], v[126:129]
	s_mov_b32 m0, s41
	v_mfma_f32_16x16x32_bf16 v[122:125], v[170:173], v[228:231], v[122:125]
	global_load_lds_dwordx4 v[204:205], off
	v_mfma_f32_16x16x32_bf16 v[118:121], v[174:177], v[228:231], v[118:121]
	s_mov_b32 m0, s45
	v_mfma_f32_16x16x32_bf16 v[114:117], v[178:181], v[228:231], v[114:117]
	global_load_lds_dwordx4 v[210:211], off
	s_waitcnt lgkmcnt(2)
	v_mfma_f32_16x16x32_bf16 v[110:113], v[154:157], v[232:235], v[110:113]
	v_mfma_f32_16x16x32_bf16 v[106:109], v[170:173], v[232:235], v[106:109]
	v_mfma_f32_16x16x32_bf16 v[102:105], v[174:177], v[232:235], v[102:105]
	v_mfma_f32_16x16x32_bf16 v[98:101], v[178:181], v[232:235], v[98:101]
	s_waitcnt lgkmcnt(1)
	v_mfma_f32_16x16x32_bf16 v[94:97], v[154:157], v[236:239], v[94:97]
	ds_read_b128 v[228:231], v245 offset:8192
	v_mfma_f32_16x16x32_bf16 v[90:93], v[170:173], v[236:239], v[90:93]
	ds_read_b128 v[232:235], v245 offset:10240
	v_mfma_f32_16x16x32_bf16 v[86:89], v[174:177], v[236:239], v[86:89]
	s_mov_b32 m0, s42
	v_mfma_f32_16x16x32_bf16 v[82:85], v[178:181], v[236:239], v[82:85]
	global_load_lds_dwordx4 v[206:207], off
	s_waitcnt lgkmcnt(2)
	v_mfma_f32_16x16x32_bf16 v[78:81], v[154:157], v[240:243], v[78:81]
	s_mov_b32 m0, s46
	v_mfma_f32_16x16x32_bf16 v[74:77], v[170:173], v[240:243], v[74:77]
	global_load_lds_dwordx4 v[212:213], off
	v_mfma_f32_16x16x32_bf16 v[70:73], v[174:177], v[240:243], v[70:73]
	v_mfma_f32_16x16x32_bf16 v[66:69], v[178:181], v[240:243], v[66:69]
	s_waitcnt lgkmcnt(1)
	v_mfma_f32_16x16x32_bf16 v[62:65], v[154:157], v[228:231], v[62:65]
	ds_read_b128 v[236:239], v245 offset:12288
	v_mfma_f32_16x16x32_bf16 v[58:61], v[170:173], v[228:231], v[58:61]
	ds_read_b128 v[240:243], v245 offset:14336
	v_mfma_f32_16x16x32_bf16 v[54:57], v[174:177], v[228:231], v[54:57]
	s_mov_b32 m0, s43
	v_mfma_f32_16x16x32_bf16 v[50:53], v[178:181], v[228:231], v[50:53]
	global_load_lds_dwordx4 v[208:209], off
	s_waitcnt lgkmcnt(2)
	v_mfma_f32_16x16x32_bf16 v[46:49], v[154:157], v[232:235], v[46:49]
	s_mov_b32 m0, s47
	v_mfma_f32_16x16x32_bf16 v[42:45], v[170:173], v[232:235], v[42:45]
	global_load_lds_dwordx4 v[214:215], off
	v_mfma_f32_16x16x32_bf16 v[34:37], v[174:177], v[232:235], v[34:37]
	v_lshl_add_u64 v[140:141], v[140:141], 0, s[10:11]
	v_mfma_f32_16x16x32_bf16 v[30:33], v[178:181], v[232:235], v[30:33]
	v_lshl_add_u64 v[142:143], v[142:143], 0, s[10:11]
	s_waitcnt lgkmcnt(1)
	v_mfma_f32_16x16x32_bf16 v[26:29], v[154:157], v[236:239], v[26:29]
	ds_read_b128 v[182:185], v246 offset:32768
	v_mfma_f32_16x16x32_bf16 v[22:25], v[170:173], v[236:239], v[22:25]
	ds_read_b128 v[186:189], v246 offset:34816
	v_mfma_f32_16x16x32_bf16 v[18:21], v[174:177], v[236:239], v[18:21]
	ds_read_b128 v[220:223], v246 offset:36864
	v_mfma_f32_16x16x32_bf16 v[14:17], v[178:181], v[236:239], v[14:17]
	ds_read_b128 v[224:227], v246 offset:38912
	s_waitcnt lgkmcnt(4)
	v_mfma_f32_16x16x32_bf16 v[10:13], v[154:157], v[240:243], v[10:13]
	ds_read_b128 v[228:231], v247
	v_mfma_f32_16x16x32_bf16 v[6:9], v[170:173], v[240:243], v[6:9]
	ds_read_b128 v[232:235], v247 offset:2048
	v_mfma_f32_16x16x32_bf16 v[2:5], v[174:177], v[240:243], v[2:5]
	v_mfma_f32_16x16x32_bf16 v[38:41], v[178:181], v[240:243], v[38:41]
	s_waitcnt lgkmcnt(1)
	v_mfma_f32_16x16x32_bf16 v[126:129], v[182:185], v[228:231], v[126:129]
	ds_read_b128 v[236:239], v247 offset:4096
	v_mfma_f32_16x16x32_bf16 v[122:125], v[186:189], v[228:231], v[122:125]
	ds_read_b128 v[240:243], v247 offset:6144
	v_mfma_f32_16x16x32_bf16 v[118:121], v[220:223], v[228:231], v[118:121]
	v_mfma_f32_16x16x32_bf16 v[114:117], v[224:227], v[228:231], v[114:117]
	s_waitcnt lgkmcnt(2)
	v_mfma_f32_16x16x32_bf16 v[110:113], v[182:185], v[232:235], v[110:113]
	v_mfma_f32_16x16x32_bf16 v[106:109], v[186:189], v[232:235], v[106:109]
	v_mfma_f32_16x16x32_bf16 v[102:105], v[220:223], v[232:235], v[102:105]
	v_mfma_f32_16x16x32_bf16 v[98:101], v[224:227], v[232:235], v[98:101]
	s_waitcnt lgkmcnt(1)
	v_mfma_f32_16x16x32_bf16 v[94:97], v[182:185], v[236:239], v[94:97]
	ds_read_b128 v[228:231], v247 offset:8192
	v_mfma_f32_16x16x32_bf16 v[90:93], v[186:189], v[236:239], v[90:93]
	ds_read_b128 v[232:235], v247 offset:10240
	v_mfma_f32_16x16x32_bf16 v[86:89], v[220:223], v[236:239], v[86:89]
	v_mfma_f32_16x16x32_bf16 v[82:85], v[224:227], v[236:239], v[82:85]
	s_waitcnt lgkmcnt(2)
; DEV unsigned cvt_pk_bf16(float lo, float hi) { const f32x2_t v = {lo, hi}; const bf16x2_t b = __builtin_convertvector(v, bf16x2_t); return __builtin_bit_cast(unsigned, b); }
; #define GLDS_STAGE(st, kt_) do { \
;         _Pragma("unroll") for (int i_ = 0; i_ < FI; ++i_) { \
;             glds16(ap + (size_t)(32 * i_) * lda + (kt_) * 64, l3a + (st) + tid * 16 + i_ * 4096); \
;             glds16(bp + (size_t)(32 * i_) * ldb + (kt_) * 64, l3a + (st) + OPB + tid * 16 + i_ * 4096); } } while (0)
; template <class Epi>
; DEV void gemm256_tile(const bf16_t* __restrict__ A, int lda, const bf16_t* __restrict__ Bt, int ldb, int K, unsigned char* lds, const Epi& epi) {
;     ...
;     for (int kt = 0; kt < nk; ++kt) {
;         const int cur = (kt & 1) * 65536;
;         asm volatile("s_waitcnt vmcnt(0)" ::: "memory");
;         __syncthreads();
;         if (kt + 1 < nk) GLDS_STAGE(cur ^ 65536, kt + 1);
; #pragma unroll
;         for (int kh = 0; kh < 2; ++kh) {
;             bf16x8 bfr[4];
;             const int ch = ((kh * 4 + fq) ^ sw) << 4;
; #pragma unroll
;             for (int i = 0; i < 4; ++i) bfr[i] = *(const bf16x8*)(lds + cur + boff + i * 2048 + ch);
; #pragma unroll
;             for (int mh = 0; mh < 2; ++mh) {
;                 bf16x8 af[4];
; #pragma unroll
;                 for (int i = 0; i < 4; ++i) af[i] = *(const bf16x8*)(lds + cur + aoff + (mh * 4 + i) * 2048 + ch);
; #pragma unroll
;                 for (int mi = 0; mi < 4; ++mi)
; #pragma unroll
;                     for (int ni = 0; ni < 4; ++ni) acc[mh * 4 + mi][ni] = __builtin_amdgcn_mfma_f32_16x16x32_bf16(bfr[ni], af[mi], acc[mh * 4 + mi][ni], 0, 0, 0);
;             }
;         }
;     }
;     ...
;     __syncthreads();
;     if constexpr (Epi::STAGE) {
; #pragma unroll
;         for (int mi = 0; mi < 8; ++mi)
; #pragma unroll
;             for (int ni = 0; ni < 4; ++ni) {
;                 const int row = wr * 128 + mi * 16 + fr, col = wc * 64 + ni * 16 + fq * 4;
;                 const f32x4 v = epi.xform(row, col, acc[mi][ni]);
;                 uint2 w; w.x = cvt_pk_bf16(v[0], v[1]); w.y = cvt_pk_bf16(v[2], v[3]);
;                 *(uint2*)(lds + row * 512 + ((((col >> 3) ^ (row & 31)) << 4) | (((col >> 2) & 1) << 3))) = w;
	v_mfma_f32_16x16x32_bf16 v[78:81], v[182:185], v[240:243], v[78:81]
	v_mfma_f32_16x16x32_bf16 v[74:77], v[186:189], v[240:243], v[74:77]
	v_mfma_f32_16x16x32_bf16 v[70:73], v[220:223], v[240:243], v[70:73]
	v_mfma_f32_16x16x32_bf16 v[66:69], v[224:227], v[240:243], v[66:69]
	s_waitcnt lgkmcnt(1)
	v_mfma_f32_16x16x32_bf16 v[62:65], v[182:185], v[228:231], v[62:65]
	ds_read_b128 v[236:239], v247 offset:12288
	v_mfma_f32_16x16x32_bf16 v[58:61], v[186:189], v[228:231], v[58:61]
	ds_read_b128 v[240:243], v247 offset:14336
	v_mfma_f32_16x16x32_bf16 v[54:57], v[220:223], v[228:231], v[54:57]
	v_mfma_f32_16x16x32_bf16 v[50:53], v[224:227], v[228:231], v[50:53]
	s_waitcnt lgkmcnt(2)
	v_mfma_f32_16x16x32_bf16 v[46:49], v[182:185], v[232:235], v[46:49]
	v_mfma_f32_16x16x32_bf16 v[42:45], v[186:189], v[232:235], v[42:45]
	v_mfma_f32_16x16x32_bf16 v[34:37], v[220:223], v[232:235], v[34:37]
	v_mfma_f32_16x16x32_bf16 v[30:33], v[224:227], v[232:235], v[30:33]
	s_waitcnt lgkmcnt(1)
	v_mfma_f32_16x16x32_bf16 v[26:29], v[182:185], v[236:239], v[26:29]
	v_mfma_f32_16x16x32_bf16 v[22:25], v[186:189], v[236:239], v[22:25]
	v_mfma_f32_16x16x32_bf16 v[18:21], v[220:223], v[236:239], v[18:21]
	v_mfma_f32_16x16x32_bf16 v[14:17], v[224:227], v[236:239], v[14:17]
	s_waitcnt lgkmcnt(0)
	v_mfma_f32_16x16x32_bf16 v[10:13], v[182:185], v[240:243], v[10:13]
	v_mfma_f32_16x16x32_bf16 v[6:9], v[186:189], v[240:243], v[6:9]
	v_mfma_f32_16x16x32_bf16 v[2:5], v[220:223], v[240:243], v[2:5]
	v_mfma_f32_16x16x32_bf16 v[38:41], v[224:227], v[240:243], v[38:41]
	s_cmp_eq_u32 s21, 0x1f0000
	s_cbranch_scc0 .LBB0_1236
	v_or_b32_e32 v186, 0x18000, v153
	v_add_u32_e32 v202, 0x10000, v151
	v_add_u32_e32 v174, v186, v152
	v_add_u32_e32 v182, v202, v152
	s_waitcnt vmcnt(0)
	s_barrier
	ds_read_b128 v[140:143], v174
	ds_read_b128 v[154:157], v174 offset:2048
	ds_read_b128 v[150:153], v182
	ds_read_b128 v[170:173], v174 offset:4096
	ds_read_b128 v[174:177], v174 offset:6144
	s_waitcnt lgkmcnt(2)
	v_mfma_f32_16x16x32_bf16 v[126:129], v[140:143], v[150:153], v[126:129]
	s_sext_i32_i8 s14, s20
	s_lshl_b32 s20, s14, 8
	s_ashr_i32 s21, s20, 31
	v_mfma_f32_16x16x32_bf16 v[122:125], v[154:157], v[150:153], v[122:125]
	s_waitcnt lgkmcnt(1)
	v_mfma_f32_16x16x32_bf16 v[118:121], v[170:173], v[150:153], v[118:121]
	s_waitcnt lgkmcnt(0)
	v_mfma_f32_16x16x32_bf16 v[114:117], v[174:177], v[150:153], v[114:117]
	ds_read_b128 v[150:153], v182 offset:2048
	s_waitcnt lgkmcnt(0)
	v_mfma_f32_16x16x32_bf16 v[110:113], v[140:143], v[150:153], v[110:113]
	v_mfma_f32_16x16x32_bf16 v[106:109], v[154:157], v[150:153], v[106:109]
	v_mfma_f32_16x16x32_bf16 v[102:105], v[170:173], v[150:153], v[102:105]
	v_mfma_f32_16x16x32_bf16 v[98:101], v[174:177], v[150:153], v[98:101]
	ds_read_b128 v[150:153], v182 offset:4096
	s_waitcnt lgkmcnt(0)
	v_mfma_f32_16x16x32_bf16 v[94:97], v[140:143], v[150:153], v[94:97]
	v_mfma_f32_16x16x32_bf16 v[90:93], v[154:157], v[150:153], v[90:93]
	v_mfma_f32_16x16x32_bf16 v[86:89], v[170:173], v[150:153], v[86:89]
	v_mfma_f32_16x16x32_bf16 v[82:85], v[174:177], v[150:153], v[82:85]
	ds_read_b128 v[150:153], v182 offset:6144
	s_waitcnt lgkmcnt(0)
	v_mfma_f32_16x16x32_bf16 v[78:81], v[140:143], v[150:153], v[78:81]
	v_mfma_f32_16x16x32_bf16 v[74:77], v[154:157], v[150:153], v[74:77]
	v_mfma_f32_16x16x32_bf16 v[70:73], v[170:173], v[150:153], v[70:73]
	v_mfma_f32_16x16x32_bf16 v[66:69], v[174:177], v[150:153], v[66:69]
	ds_read_b128 v[150:153], v182 offset:8192
	ds_read_b128 v[178:181], v182 offset:10240
	s_waitcnt lgkmcnt(1)
	v_mfma_f32_16x16x32_bf16 v[62:65], v[140:143], v[150:153], v[62:65]
	v_mfma_f32_16x16x32_bf16 v[58:61], v[154:157], v[150:153], v[58:61]
	v_mfma_f32_16x16x32_bf16 v[54:57], v[170:173], v[150:153], v[54:57]
	v_mfma_f32_16x16x32_bf16 v[50:53], v[174:177], v[150:153], v[50:53]
	ds_read_b128 v[150:153], v182 offset:12288
	s_waitcnt lgkmcnt(1)
	v_mfma_f32_16x16x32_bf16 v[46:49], v[140:143], v[178:181], v[46:49]
	v_mfma_f32_16x16x32_bf16 v[42:45], v[154:157], v[178:181], v[42:45]
	v_mfma_f32_16x16x32_bf16 v[34:37], v[170:173], v[178:181], v[34:37]
	v_mfma_f32_16x16x32_bf16 v[30:33], v[174:177], v[178:181], v[30:33]
	ds_read_b128 v[178:181], v182 offset:14336
	s_waitcnt lgkmcnt(1)
	v_mfma_f32_16x16x32_bf16 v[182:185], v[140:143], v[150:153], v[26:29]
	s_nop 2
	v_add_u32_e32 v29, v186, v149
	ds_read_b128 v[186:189], v29
	ds_read_b128 v[190:193], v29 offset:2048
	ds_read_b128 v[194:197], v29 offset:4096
	ds_read_b128 v[198:201], v29 offset:6144
	v_add_u32_e32 v29, v202, v149
	v_mfma_f32_16x16x32_bf16 v[22:25], v[154:157], v[150:153], v[22:25]
	v_and_b32_e32 v28, 0xc0, v144
	v_lshl_or_b32 v147, v147, 2, v28
	v_lshlrev_b32_e32 v28, 3, v146
	v_mfma_f32_16x16x32_bf16 v[18:21], v[170:173], v[150:153], v[18:21]
	v_lshl_add_u64 v[26:27], v[132:133], 0, s[12:13]
	v_lshl_add_u64 v[26:27], s[20:21], 1, v[26:27]
	s_mov_b32 s12, 0
	v_mfma_f32_16x16x32_bf16 v[14:17], v[174:177], v[150:153], v[14:17]
	ds_read_b128 v[150:153], v29
	ds_read_b128 v[202:205], v29 offset:2048
	ds_read_b128 v[206:209], v29 offset:4096
	ds_read_b128 v[210:213], v29 offset:6144
	s_waitcnt lgkmcnt(3)
	v_mfma_f32_16x16x32_bf16 v[126:129], v[186:189], v[150:153], v[126:129]
	v_mfma_f32_16x16x32_bf16 v[122:125], v[190:193], v[150:153], v[122:125]
	s_waitcnt lgkmcnt(1)
	v_mfma_f32_16x16x32_bf16 v[94:97], v[186:189], v[206:209], v[94:97]
	v_mfma_f32_16x16x32_bf16 v[10:13], v[140:143], v[178:181], v[10:13]
	ds_read_b128 v[140:143], v29 offset:8192
	ds_read_b128 v[214:217], v29 offset:10240
	ds_read_b128 v[218:221], v29 offset:12288
	ds_read_b128 v[222:225], v29 offset:14336
	v_lshlrev_b32_e32 v29, 9, v148
	v_and_or_b32 v146, v28, 8, v29
	v_mfma_f32_16x16x32_bf16 v[118:121], v[194:197], v[150:153], v[118:121]
	v_cvt_pk_bf16_f32 v28, v126, v127
	v_lshrrev_b32_e32 v126, 3, v147
	v_xor_b32_e32 v127, v126, v145
	v_mfma_f32_16x16x32_bf16 v[90:93], v[190:193], v[206:209], v[90:93]
	v_cvt_pk_bf16_f32 v29, v128, v129
	v_lshl_or_b32 v127, v127, 4, v146
	v_cvt_pk_bf16_f32 v122, v122, v123
	v_mfma_f32_16x16x32_bf16 v[114:117], v[198:201], v[150:153], v[114:117]
	v_cvt_pk_bf16_f32 v123, v124, v125
	v_bitop3_b32 v124, v126, v145, 2 bitop3:0x36
	v_cvt_pk_bf16_f32 v94, v94, v95
	v_mfma_f32_16x16x32_bf16 v[86:89], v[194:197], v[206:209], v[86:89]
	v_cvt_pk_bf16_f32 v95, v96, v97
	s_waitcnt lgkmcnt(0)
	s_barrier
; DEV unsigned cvt_pk_bf16(float lo, float hi) { const f32x2_t v = {lo, hi}; const bf16x2_t b = __builtin_convertvector(v, bf16x2_t); return __builtin_bit_cast(unsigned, b); }
; template <class Epi>
; DEV void gemm256_tile(const bf16_t* __restrict__ A, int lda, const bf16_t* __restrict__ Bt, int ldb, int K, unsigned char* lds, const Epi& epi) {
;     ...
;                 for (int mi = 0; mi < 4; ++mi)
; #pragma unroll
;                     for (int ni = 0; ni < 4; ++ni) acc[mh * 4 + mi][ni] = __builtin_amdgcn_mfma_f32_16x16x32_bf16(bfr[ni], af[mi], acc[mh * 4 + mi][ni], 0, 0, 0);
;             }
;         }
;     }
;     ...
;     __syncthreads();
;     if constexpr (Epi::STAGE) {
; #pragma unroll
;         for (int mi = 0; mi < 8; ++mi)
; #pragma unroll
;             for (int ni = 0; ni < 4; ++ni) {
;                 const int row = wr * 128 + mi * 16 + fr, col = wc * 64 + ni * 16 + fq * 4;
;                 const f32x4 v = epi.xform(row, col, acc[mi][ni]);
;                 uint2 w; w.x = cvt_pk_bf16(v[0], v[1]); w.y = cvt_pk_bf16(v[2], v[3]);
;                 *(uint2*)(lds + row * 512 + ((((col >> 3) ^ (row & 31)) << 4) | (((col >> 2) & 1) << 3))) = w;
;             }
;         __syncthreads();
	v_mfma_f32_16x16x32_bf16 v[110:113], v[186:189], v[202:205], v[110:113]
	v_lshl_add_u32 v124, v124, 4, v146
	v_cvt_pk_bf16_f32 v118, v118, v119
	v_mfma_f32_16x16x32_bf16 v[82:85], v[198:201], v[206:209], v[82:85]
	v_cvt_pk_bf16_f32 v119, v120, v121
	v_bitop3_b32 v120, v126, v145, 4 bitop3:0x36
	ds_write2st64_b64 v127, v[28:29], v[94:95] offset1:32
	v_mfma_f32_16x16x32_bf16 v[106:109], v[190:193], v[202:205], v[106:109]
	v_cvt_pk_bf16_f32 v28, v90, v91
	v_cvt_pk_bf16_f32 v29, v92, v93
	v_lshl_add_u32 v120, v120, 4, v146
	v_mfma_f32_16x16x32_bf16 v[78:81], v[186:189], v[210:213], v[78:81]
	v_cvt_pk_bf16_f32 v114, v114, v115
	v_cvt_pk_bf16_f32 v115, v116, v117
	v_bitop3_b32 v116, v126, v145, 6 bitop3:0x36
	v_mfma_f32_16x16x32_bf16 v[102:105], v[194:197], v[202:205], v[102:105]
	ds_write2st64_b64 v124, v[122:123], v[28:29] offset1:32
	v_cvt_pk_bf16_f32 v28, v86, v87
	v_cvt_pk_bf16_f32 v29, v88, v89
	v_mfma_f32_16x16x32_bf16 v[74:77], v[190:193], v[210:213], v[74:77]
	v_lshl_add_u32 v116, v116, 4, v146
	v_or_b32_e32 v117, 16, v145
	v_cvt_pk_bf16_f32 v110, v110, v111
	v_mfma_f32_16x16x32_bf16 v[2:5], v[170:173], v[178:181], v[2:5]
	v_cvt_pk_bf16_f32 v111, v112, v113
	v_bitop3_b32 v112, v126, v145, 16 bitop3:0x1e
	ds_write2st64_b64 v120, v[118:119], v[28:29] offset1:32
	v_mfma_f32_16x16x32_bf16 v[98:101], v[198:201], v[202:205], v[98:101]
	v_cvt_pk_bf16_f32 v28, v82, v83
	v_cvt_pk_bf16_f32 v29, v84, v85
	v_lshl_or_b32 v112, v112, 4, v146
	v_mfma_f32_16x16x32_bf16 v[70:73], v[194:197], v[210:213], v[70:73]
	v_cvt_pk_bf16_f32 v106, v106, v107
	v_cvt_pk_bf16_f32 v107, v108, v109
	v_bitop3_b32 v108, v126, v117, 2 bitop3:0x36
	v_mfma_f32_16x16x32_bf16 v[66:69], v[198:201], v[210:213], v[66:69]
	ds_write2st64_b64 v116, v[114:115], v[28:29] offset1:32
	v_cvt_pk_bf16_f32 v28, v78, v79
	v_cvt_pk_bf16_f32 v29, v80, v81
	v_lshl_add_u32 v108, v108, 4, v146
	v_cvt_pk_bf16_f32 v102, v102, v103
	v_cvt_pk_bf16_f32 v103, v104, v105
	v_bitop3_b32 v104, v126, v117, 4 bitop3:0x36
	ds_write2st64_b64 v112, v[110:111], v[28:29] offset0:16 offset1:48
	v_cvt_pk_bf16_f32 v28, v74, v75
	v_cvt_pk_bf16_f32 v29, v76, v77
	v_lshl_add_u32 v104, v104, 4, v146
	v_cvt_pk_bf16_f32 v98, v98, v99
	v_cvt_pk_bf16_f32 v99, v100, v101
	v_bitop3_b32 v100, v126, v117, 6 bitop3:0x36
	ds_write2st64_b64 v108, v[106:107], v[28:29] offset0:16 offset1:48
	v_cvt_pk_bf16_f32 v28, v70, v71
	v_cvt_pk_bf16_f32 v29, v72, v73
	v_mfma_f32_16x16x32_bf16 v[34:37], v[194:197], v[214:217], v[34:37]
	v_lshl_add_u32 v100, v100, 4, v146
	ds_write2st64_b64 v104, v[102:103], v[28:29] offset0:16 offset1:48
	v_cvt_pk_bf16_f32 v28, v66, v67
	v_mfma_f32_16x16x32_bf16 v[2:5], v[194:197], v[222:225], v[2:5]
	v_cvt_pk_bf16_f32 v29, v68, v69
	ds_write2st64_b64 v100, v[98:99], v[28:29] offset0:16 offset1:48
	s_nop 1
	v_cvt_pk_bf16_f32 v34, v34, v35
	v_mfma_f32_16x16x32_bf16 v[38:41], v[174:177], v[178:181], v[38:41]
	v_cvt_pk_bf16_f32 v35, v36, v37
	s_nop 0
	v_cvt_pk_bf16_f32 v2, v2, v3
	v_cvt_pk_bf16_f32 v3, v4, v5
	v_mfma_f32_16x16x32_bf16 v[6:9], v[154:157], v[178:181], v[6:9]
	ds_write2st64_b64 v104, v[34:35], v[2:3] offset0:80 offset1:112
	v_mfma_f32_16x16x32_bf16 v[28:31], v[198:201], v[214:217], v[30:33]
	v_mfma_f32_16x16x32_bf16 v[2:5], v[198:201], v[222:225], v[38:41]
	v_mfma_f32_16x16x32_bf16 v[62:65], v[186:189], v[140:143], v[62:65]
	s_nop 5
	v_cvt_pk_bf16_f32 v32, v28, v29
	v_cvt_pk_bf16_f32 v33, v30, v31
	v_cvt_pk_bf16_f32 v2, v2, v3
	v_mfma_f32_16x16x32_bf16 v[58:61], v[190:193], v[140:143], v[58:61]
	v_cvt_pk_bf16_f32 v3, v4, v5
	v_cvt_pk_bf16_f32 v62, v62, v63
	v_cvt_pk_bf16_f32 v63, v64, v65
	v_mfma_f32_16x16x32_bf16 v[54:57], v[194:197], v[140:143], v[54:57]
	ds_write2st64_b64 v100, v[32:33], v[2:3] offset0:80 offset1:112
	s_nop 2
	v_cvt_pk_bf16_f32 v58, v58, v59
	v_cvt_pk_bf16_f32 v59, v60, v61
	v_mfma_f32_16x16x32_bf16 v[50:53], v[198:201], v[140:143], v[50:53]
	v_and_b32_e32 v2, 0x1f0, v138
	v_cvt_pk_bf16_f32 v54, v54, v55
	v_cvt_pk_bf16_f32 v55, v56, v57
	v_mfma_f32_16x16x32_bf16 v[46:49], v[186:189], v[214:217], v[46:49]
	v_mfma_f32_16x16x32_bf16 v[42:45], v[190:193], v[214:217], v[42:45]
	s_nop 2
	v_cvt_pk_bf16_f32 v50, v50, v51
	v_cvt_pk_bf16_f32 v51, v52, v53
	s_nop 1
	v_cvt_pk_bf16_f32 v46, v46, v47
	v_mfma_f32_16x16x32_bf16 v[28:31], v[186:189], v[218:221], v[182:185]
	v_cvt_pk_bf16_f32 v47, v48, v49
	v_cvt_pk_bf16_f32 v42, v42, v43
	v_cvt_pk_bf16_f32 v43, v44, v45
	v_mfma_f32_16x16x32_bf16 v[22:25], v[190:193], v[218:221], v[22:25]
	v_mfma_f32_16x16x32_bf16 v[18:21], v[194:197], v[218:221], v[18:21]
	s_nop 2
	v_cvt_pk_bf16_f32 v28, v28, v29
	v_cvt_pk_bf16_f32 v29, v30, v31
	s_nop 1
	v_cvt_pk_bf16_f32 v22, v22, v23
	v_mfma_f32_16x16x32_bf16 v[14:17], v[198:201], v[218:221], v[14:17]
	v_cvt_pk_bf16_f32 v23, v24, v25
	v_cvt_pk_bf16_f32 v18, v18, v19
	v_cvt_pk_bf16_f32 v19, v20, v21
	v_mfma_f32_16x16x32_bf16 v[10:13], v[186:189], v[222:225], v[10:13]
	ds_write2st64_b64 v127, v[62:63], v[28:29] offset0:64 offset1:96
	s_nop 2
	v_cvt_pk_bf16_f32 v14, v14, v15
	v_cvt_pk_bf16_f32 v15, v16, v17
	v_mfma_f32_16x16x32_bf16 v[6:9], v[190:193], v[222:225], v[6:9]
	ds_write2st64_b64 v124, v[58:59], v[22:23] offset0:64 offset1:96
	v_cvt_pk_bf16_f32 v10, v10, v11
	v_cvt_pk_bf16_f32 v11, v12, v13
	ds_write2st64_b64 v120, v[54:55], v[18:19] offset0:64 offset1:96
	ds_write2st64_b64 v116, v[50:51], v[14:15] offset0:64 offset1:96
	s_nop 2
	v_cvt_pk_bf16_f32 v6, v6, v7
	v_cvt_pk_bf16_f32 v7, v8, v9
	ds_write2st64_b64 v112, v[46:47], v[10:11] offset0:80 offset1:112
	ds_write2st64_b64 v108, v[42:43], v[6:7] offset0:80 offset1:112
	s_waitcnt lgkmcnt(0)
	s_barrier

; #define GLDS_STAGE(st, kt_) do { \
;         _Pragma("unroll") for (int i_ = 0; i_ < FI; ++i_) { \
;             glds16(ap + (size_t)(32 * i_) * lda + (kt_) * 64, l3a + (st) + tid * 16 + i_ * 4096); \
;             glds16(bp + (size_t)(32 * i_) * ldb + (kt_) * 64, l3a + (st) + OPB + tid * 16 + i_ * 4096); } } while (0)
; #define GLDS_STAGE(st, kt_) do { \
;         _Pragma("unroll") for (int i_ = 0; i_ < 4; ++i_) { \
;             glds16(ap + (size_t)(64 * i_) * lda + (kt_) * 64, l3a + (st) + tid * 16 + i_ * 8192); \
;             glds16(bp + (size_t)(64 * i_) * ldb + (kt_) * 64, l3a + (st) + 32768 + tid * 16 + i_ * 8192); } } while (0)
; template <class Epi>
; DEV void gemm256_tile(const bf16_t* __restrict__ A, int lda, const bf16_t* __restrict__ Bt, int ldb, int K, unsigned char* lds, const Epi& epi) {
;     ...
;     GLDS_STAGE(0, 0);
;     const int aoff = (wr * 128 + fr) * 128, boff = 32768 + (wc * 64 + fr) * 128, sw = fr & 7;
;     for (int kt = 0; kt < nk; ++kt) {
;         const int cur = (kt & 1) * 65536;
;         asm volatile("s_waitcnt vmcnt(0)" ::: "memory");
;         __syncthreads();
;         if (kt + 1 < nk) GLDS_STAGE(cur ^ 65536, kt + 1);
; #pragma unroll
;         for (int kh = 0; kh < 2; ++kh) {
;             bf16x8 bfr[4];
;             const int ch = ((kh * 4 + fq) ^ sw) << 4;
; #pragma unroll
;             for (int i = 0; i < 4; ++i) bfr[i] = *(const bf16x8*)(lds + cur + boff + i * 2048 + ch);
; #pragma unroll
;             for (int mh = 0; mh < 2; ++mh) {
;                 bf16x8 af[4];
; #pragma unroll
;                 for (int i = 0; i < 4; ++i) af[i] = *(const bf16x8*)(lds + cur + aoff + (mh * 4 + i) * 2048 + ch);
; #pragma unroll
;                 for (int mi = 0; mi < 4; ++mi)
; #pragma unroll
;                     for (int ni = 0; ni < 4; ++ni) acc[mh * 4 + mi][ni] = __builtin_amdgcn_mfma_f32_16x16x32_bf16(bfr[ni], af[mi], acc[mh * 4 + mi][ni], 0, 0, 0);
.LBB0_1466:
	s_and_b32 s48, s21, 0x10000
	s_xor_b32 s49, s48, 0x10000
	v_add_u32_e32 v216, s49, v140
	v_add_u32_e32 v217, s49, v153
	s_waitcnt vmcnt(0) lgkmcnt(0)
	s_barrier
	v_or_b32_e32 v248, s48, v155
	v_add_u32_e32 v249, s48, v152
	v_add_u32_e32 v244, v248, v154
	v_add_u32_e32 v245, v249, v154
	ds_read_b128 v[162:165], v244 offset:32768
	ds_read_b128 v[166:169], v244 offset:34816
	ds_read_b128 v[170:173], v244 offset:36864
	ds_read_b128 v[174:177], v244 offset:38912
	ds_read_b128 v[228:231], v245
	ds_read_b128 v[232:235], v245 offset:2048
	ds_read_b128 v[236:239], v245 offset:4096
	ds_read_b128 v[240:243], v245 offset:6144
	v_readfirstlane_b32 s40, v216
	v_readfirstlane_b32 s44, v217
	v_add_u32_e32 v246, v248, v151
	v_add_u32_e32 v247, v249, v151
	s_mov_b32 m0, s40
	v_lshl_add_u64 v[204:205], v[142:143], 0, s[4:5]
	global_load_lds_dwordx4 v[142:143], off
	s_mov_b32 m0, s44
	v_lshl_add_u64 v[210:211], v[144:145], 0, s[4:5]
	global_load_lds_dwordx4 v[144:145], off
	s_add_i32 s41, s40, 0x2000
	s_add_i32 s45, s44, 0x2000
	s_add_i32 s42, s40, 0x4000
	s_add_i32 s46, s44, 0x4000
	s_add_i32 s43, s40, 0x6000
	s_add_i32 s47, s44, 0x6000
	s_add_i32 s21, s21, 0x10000
	v_lshl_add_u64 v[206:207], v[142:143], 0, s[6:7]
	v_lshl_add_u64 v[212:213], v[144:145], 0, s[6:7]
	v_lshl_add_u64 v[208:209], v[142:143], 0, s[8:9]
	v_lshl_add_u64 v[214:215], v[144:145], 0, s[8:9]
	s_waitcnt lgkmcnt(3)
	v_mfma_f32_16x16x32_bf16 v[126:129], v[162:165], v[228:231], v[126:129]
	s_mov_b32 m0, s41
	v_mfma_f32_16x16x32_bf16 v[122:125], v[166:169], v[228:231], v[122:125]
	global_load_lds_dwordx4 v[204:205], off
	v_mfma_f32_16x16x32_bf16 v[118:121], v[170:173], v[228:231], v[118:121]
	s_mov_b32 m0, s45
	v_mfma_f32_16x16x32_bf16 v[114:117], v[174:177], v[228:231], v[114:117]
	global_load_lds_dwordx4 v[210:211], off
	s_waitcnt lgkmcnt(2)
	v_mfma_f32_16x16x32_bf16 v[110:113], v[162:165], v[232:235], v[110:113]
	v_mfma_f32_16x16x32_bf16 v[106:109], v[166:169], v[232:235], v[106:109]
	v_mfma_f32_16x16x32_bf16 v[102:105], v[170:173], v[232:235], v[102:105]
	v_mfma_f32_16x16x32_bf16 v[98:101], v[174:177], v[232:235], v[98:101]
	s_waitcnt lgkmcnt(1)
	v_mfma_f32_16x16x32_bf16 v[94:97], v[162:165], v[236:239], v[94:97]
	ds_read_b128 v[228:231], v245 offset:8192
	v_mfma_f32_16x16x32_bf16 v[90:93], v[166:169], v[236:239], v[90:93]
	ds_read_b128 v[232:235], v245 offset:10240
	v_mfma_f32_16x16x32_bf16 v[86:89], v[170:173], v[236:239], v[86:89]
	s_mov_b32 m0, s42
	v_mfma_f32_16x16x32_bf16 v[82:85], v[174:177], v[236:239], v[82:85]
	global_load_lds_dwordx4 v[206:207], off
	s_waitcnt lgkmcnt(2)
	v_mfma_f32_16x16x32_bf16 v[78:81], v[162:165], v[240:243], v[78:81]
	s_mov_b32 m0, s46
	v_mfma_f32_16x16x32_bf16 v[74:77], v[166:169], v[240:243], v[74:77]
	global_load_lds_dwordx4 v[212:213], off
	v_mfma_f32_16x16x32_bf16 v[70:73], v[170:173], v[240:243], v[70:73]
	v_mfma_f32_16x16x32_bf16 v[66:69], v[174:177], v[240:243], v[66:69]
	s_waitcnt lgkmcnt(1)
	v_mfma_f32_16x16x32_bf16 v[62:65], v[162:165], v[228:231], v[62:65]
	ds_read_b128 v[236:239], v245 offset:12288
	v_mfma_f32_16x16x32_bf16 v[58:61], v[166:169], v[228:231], v[58:61]
	ds_read_b128 v[240:243], v245 offset:14336
	v_mfma_f32_16x16x32_bf16 v[54:57], v[170:173], v[228:231], v[54:57]
	s_mov_b32 m0, s43
	v_mfma_f32_16x16x32_bf16 v[50:53], v[174:177], v[228:231], v[50:53]
	global_load_lds_dwordx4 v[208:209], off
	s_waitcnt lgkmcnt(2)
	v_mfma_f32_16x16x32_bf16 v[46:49], v[162:165], v[232:235], v[46:49]
	s_mov_b32 m0, s47
	v_mfma_f32_16x16x32_bf16 v[42:45], v[166:169], v[232:235], v[42:45]
	global_load_lds_dwordx4 v[214:215], off
	v_mfma_f32_16x16x32_bf16 v[34:37], v[170:173], v[232:235], v[34:37]
	v_lshl_add_u64 v[142:143], v[142:143], 0, s[10:11]
	v_mfma_f32_16x16x32_bf16 v[30:33], v[174:177], v[232:235], v[30:33]
	v_lshl_add_u64 v[144:145], v[144:145], 0, s[10:11]
	s_waitcnt lgkmcnt(1)
	v_mfma_f32_16x16x32_bf16 v[26:29], v[162:165], v[236:239], v[26:29]
	ds_read_b128 v[178:181], v246 offset:32768
	v_mfma_f32_16x16x32_bf16 v[22:25], v[166:169], v[236:239], v[22:25]
	ds_read_b128 v[182:185], v246 offset:34816
	v_mfma_f32_16x16x32_bf16 v[18:21], v[170:173], v[236:239], v[18:21]
	ds_read_b128 v[220:223], v246 offset:36864
	v_mfma_f32_16x16x32_bf16 v[14:17], v[174:177], v[236:239], v[14:17]
	ds_read_b128 v[224:227], v246 offset:38912
	s_waitcnt lgkmcnt(4)
	v_mfma_f32_16x16x32_bf16 v[10:13], v[162:165], v[240:243], v[10:13]
	ds_read_b128 v[228:231], v247
	v_mfma_f32_16x16x32_bf16 v[6:9], v[166:169], v[240:243], v[6:9]
	ds_read_b128 v[232:235], v247 offset:2048
	v_mfma_f32_16x16x32_bf16 v[2:5], v[170:173], v[240:243], v[2:5]
	v_mfma_f32_16x16x32_bf16 v[38:41], v[174:177], v[240:243], v[38:41]
	s_waitcnt lgkmcnt(1)
	v_mfma_f32_16x16x32_bf16 v[126:129], v[178:181], v[228:231], v[126:129]
	ds_read_b128 v[236:239], v247 offset:4096
	v_mfma_f32_16x16x32_bf16 v[122:125], v[182:185], v[228:231], v[122:125]
	ds_read_b128 v[240:243], v247 offset:6144
	v_mfma_f32_16x16x32_bf16 v[118:121], v[220:223], v[228:231], v[118:121]
	v_mfma_f32_16x16x32_bf16 v[114:117], v[224:227], v[228:231], v[114:117]
	s_waitcnt lgkmcnt(2)
	v_mfma_f32_16x16x32_bf16 v[110:113], v[178:181], v[232:235], v[110:113]
	v_mfma_f32_16x16x32_bf16 v[106:109], v[182:185], v[232:235], v[106:109]
	v_mfma_f32_16x16x32_bf16 v[102:105], v[220:223], v[232:235], v[102:105]
	v_mfma_f32_16x16x32_bf16 v[98:101], v[224:227], v[232:235], v[98:101]
	s_waitcnt lgkmcnt(1)
	v_mfma_f32_16x16x32_bf16 v[94:97], v[178:181], v[236:239], v[94:97]
	ds_read_b128 v[228:231], v247 offset:8192
	v_mfma_f32_16x16x32_bf16 v[90:93], v[182:185], v[236:239], v[90:93]
	ds_read_b128 v[232:235], v247 offset:10240
	v_mfma_f32_16x16x32_bf16 v[86:89], v[220:223], v[236:239], v[86:89]
	v_mfma_f32_16x16x32_bf16 v[82:85], v[224:227], v[236:239], v[82:85]
	s_waitcnt lgkmcnt(2)
; DEV unsigned cvt_pk_bf16(float lo, float hi) { const f32x2_t v = {lo, hi}; const bf16x2_t b = __builtin_convertvector(v, bf16x2_t); return __builtin_bit_cast(unsigned, b); }
; #define GLDS_STAGE(st, kt_) do { \
;         _Pragma("unroll") for (int i_ = 0; i_ < FI; ++i_) { \
;             glds16(ap + (size_t)(32 * i_) * lda + (kt_) * 64, l3a + (st) + tid * 16 + i_ * 4096); \
;             glds16(bp + (size_t)(32 * i_) * ldb + (kt_) * 64, l3a + (st) + OPB + tid * 16 + i_ * 4096); } } while (0)
; template <class Epi>
; DEV void gemm256_tile(const bf16_t* __restrict__ A, int lda, const bf16_t* __restrict__ Bt, int ldb, int K, unsigned char* lds, const Epi& epi) {
;     ...
;     for (int kt = 0; kt < nk; ++kt) {
;         const int cur = (kt & 1) * 65536;
;         asm volatile("s_waitcnt vmcnt(0)" ::: "memory");
;         __syncthreads();
;         if (kt + 1 < nk) GLDS_STAGE(cur ^ 65536, kt + 1);
; #pragma unroll
;         for (int kh = 0; kh < 2; ++kh) {
;             bf16x8 bfr[4];
;             const int ch = ((kh * 4 + fq) ^ sw) << 4;
; #pragma unroll
;             for (int i = 0; i < 4; ++i) bfr[i] = *(const bf16x8*)(lds + cur + boff + i * 2048 + ch);
; #pragma unroll
;             for (int mh = 0; mh < 2; ++mh) {
;                 bf16x8 af[4];
; #pragma unroll
;                 for (int i = 0; i < 4; ++i) af[i] = *(const bf16x8*)(lds + cur + aoff + (mh * 4 + i) * 2048 + ch);
; #pragma unroll
;                 for (int mi = 0; mi < 4; ++mi)
; #pragma unroll
;                     for (int ni = 0; ni < 4; ++ni) acc[mh * 4 + mi][ni] = __builtin_amdgcn_mfma_f32_16x16x32_bf16(bfr[ni], af[mi], acc[mh * 4 + mi][ni], 0, 0, 0);
;             }
;         }
;     }
;     ...
;     __syncthreads();
;     if constexpr (Epi::STAGE) {
; #pragma unroll
;         for (int mi = 0; mi < 8; ++mi)
; #pragma unroll
;             for (int ni = 0; ni < 4; ++ni) {
;                 const int row = wr * 128 + mi * 16 + fr, col = wc * 64 + ni * 16 + fq * 4;
;                 const f32x4 v = epi.xform(row, col, acc[mi][ni]);
;                 uint2 w; w.x = cvt_pk_bf16(v[0], v[1]); w.y = cvt_pk_bf16(v[2], v[3]);
;                 *(uint2*)(lds + row * 512 + ((((col >> 3) ^ (row & 31)) << 4) | (((col >> 2) & 1) << 3))) = w;
	v_mfma_f32_16x16x32_bf16 v[78:81], v[178:181], v[240:243], v[78:81]
	v_mfma_f32_16x16x32_bf16 v[74:77], v[182:185], v[240:243], v[74:77]
	v_mfma_f32_16x16x32_bf16 v[70:73], v[220:223], v[240:243], v[70:73]
	v_mfma_f32_16x16x32_bf16 v[66:69], v[224:227], v[240:243], v[66:69]
	s_waitcnt lgkmcnt(1)
	v_mfma_f32_16x16x32_bf16 v[62:65], v[178:181], v[228:231], v[62:65]
	ds_read_b128 v[236:239], v247 offset:12288
	v_mfma_f32_16x16x32_bf16 v[58:61], v[182:185], v[228:231], v[58:61]
	ds_read_b128 v[240:243], v247 offset:14336
	v_mfma_f32_16x16x32_bf16 v[54:57], v[220:223], v[228:231], v[54:57]
	v_mfma_f32_16x16x32_bf16 v[50:53], v[224:227], v[228:231], v[50:53]
	s_waitcnt lgkmcnt(2)
	v_mfma_f32_16x16x32_bf16 v[46:49], v[178:181], v[232:235], v[46:49]
	v_mfma_f32_16x16x32_bf16 v[42:45], v[182:185], v[232:235], v[42:45]
	v_mfma_f32_16x16x32_bf16 v[34:37], v[220:223], v[232:235], v[34:37]
	v_mfma_f32_16x16x32_bf16 v[30:33], v[224:227], v[232:235], v[30:33]
	s_waitcnt lgkmcnt(1)
	v_mfma_f32_16x16x32_bf16 v[26:29], v[178:181], v[236:239], v[26:29]
	v_mfma_f32_16x16x32_bf16 v[22:25], v[182:185], v[236:239], v[22:25]
	v_mfma_f32_16x16x32_bf16 v[18:21], v[220:223], v[236:239], v[18:21]
	v_mfma_f32_16x16x32_bf16 v[14:17], v[224:227], v[236:239], v[14:17]
	s_waitcnt lgkmcnt(0)
	v_mfma_f32_16x16x32_bf16 v[10:13], v[178:181], v[240:243], v[10:13]
	v_mfma_f32_16x16x32_bf16 v[6:9], v[182:185], v[240:243], v[6:9]
	v_mfma_f32_16x16x32_bf16 v[2:5], v[220:223], v[240:243], v[2:5]
	v_mfma_f32_16x16x32_bf16 v[38:41], v[224:227], v[240:243], v[38:41]
	s_cmp_eq_u32 s21, 0x1f0000
	s_cbranch_scc0 .LBB0_1466
	v_or_b32_e32 v184, 0x18000, v155
	v_add_u32_e32 v156, v184, v154
	s_waitcnt vmcnt(0)
	s_barrier
	ds_read_b128 v[142:145], v156
	ds_read_b128 v[162:165], v156 offset:2048
	ds_read_b128 v[166:169], v156 offset:4096
	ds_read_b128 v[170:173], v156 offset:6144
	v_add_u32_e32 v198, 0x10000, v152
	v_add_u32_e32 v178, v198, v154
	ds_read_b128 v[152:155], v178
	s_waitcnt lgkmcnt(0)
	v_mfma_f32_16x16x32_bf16 v[126:129], v[142:145], v[152:155], v[126:129]
	s_sext_i32_i8 s14, s20
	s_lshl_b32 s20, s14, 8
	s_ashr_i32 s21, s20, 31
	v_mfma_f32_16x16x32_bf16 v[122:125], v[162:165], v[152:155], v[122:125]
	v_lshl_add_u64 v[156:157], v[134:135], 0, s[12:13]
	v_lshl_add_u64 v[182:183], v[130:131], 0, s[12:13]
	s_lshl_b64 s[12:13], s[20:21], 1
	v_mfma_f32_16x16x32_bf16 v[118:121], v[166:169], v[152:155], v[118:121]
	v_lshlrev_b32_e32 v148, 3, v148
	v_lshlrev_b32_e32 v150, 9, v150
	v_and_or_b32 v148, v148, 8, v150
	v_mfma_f32_16x16x32_bf16 v[114:117], v[170:173], v[152:155], v[114:117]
	ds_read_b128 v[152:155], v178 offset:2048
	s_waitcnt lgkmcnt(0)
	v_mfma_f32_16x16x32_bf16 v[110:113], v[142:145], v[152:155], v[110:113]
	v_mfma_f32_16x16x32_bf16 v[106:109], v[162:165], v[152:155], v[106:109]
	v_mfma_f32_16x16x32_bf16 v[102:105], v[166:169], v[152:155], v[102:105]
	v_mfma_f32_16x16x32_bf16 v[98:101], v[170:173], v[152:155], v[98:101]
	ds_read_b128 v[152:155], v178 offset:4096
	s_waitcnt lgkmcnt(0)
	v_mfma_f32_16x16x32_bf16 v[94:97], v[142:145], v[152:155], v[94:97]
	v_mfma_f32_16x16x32_bf16 v[90:93], v[162:165], v[152:155], v[90:93]
	v_mfma_f32_16x16x32_bf16 v[86:89], v[166:169], v[152:155], v[86:89]
	v_mfma_f32_16x16x32_bf16 v[82:85], v[170:173], v[152:155], v[82:85]
	ds_read_b128 v[152:155], v178 offset:6144
	s_waitcnt lgkmcnt(0)
	v_mfma_f32_16x16x32_bf16 v[78:81], v[142:145], v[152:155], v[78:81]
	v_mfma_f32_16x16x32_bf16 v[74:77], v[162:165], v[152:155], v[74:77]
	v_mfma_f32_16x16x32_bf16 v[70:73], v[166:169], v[152:155], v[70:73]
	v_mfma_f32_16x16x32_bf16 v[66:69], v[170:173], v[152:155], v[66:69]
	ds_read_b128 v[152:155], v178 offset:8192
	ds_read_b128 v[174:177], v178 offset:10240
	s_waitcnt lgkmcnt(1)
	v_mfma_f32_16x16x32_bf16 v[62:65], v[142:145], v[152:155], v[62:65]
	v_mfma_f32_16x16x32_bf16 v[58:61], v[162:165], v[152:155], v[58:61]
	v_mfma_f32_16x16x32_bf16 v[54:57], v[166:169], v[152:155], v[54:57]
	v_mfma_f32_16x16x32_bf16 v[50:53], v[170:173], v[152:155], v[50:53]
	ds_read_b128 v[152:155], v178 offset:12288
	s_waitcnt lgkmcnt(1)
	v_mfma_f32_16x16x32_bf16 v[46:49], v[142:145], v[174:177], v[46:49]
	v_mfma_f32_16x16x32_bf16 v[42:45], v[162:165], v[174:177], v[42:45]
	v_mfma_f32_16x16x32_bf16 v[34:37], v[166:169], v[174:177], v[34:37]
	v_mfma_f32_16x16x32_bf16 v[30:33], v[170:173], v[174:177], v[30:33]
	ds_read_b128 v[174:177], v178 offset:14336
	s_waitcnt lgkmcnt(1)
	v_mfma_f32_16x16x32_bf16 v[178:181], v[142:145], v[152:155], v[26:29]
	s_nop 2
	v_lshl_add_u64 v[28:29], v[156:157], 0, s[12:13]
	v_add_u32_e32 v157, v184, v151
	v_lshl_add_u64 v[26:27], v[182:183], 0, s[12:13]
	ds_read_b128 v[182:185], v157
	ds_read_b128 v[186:189], v157 offset:2048
	ds_read_b128 v[190:193], v157 offset:4096
	ds_read_b128 v[194:197], v157 offset:6144
	v_add_u32_e32 v151, v198, v151
	v_mfma_f32_16x16x32_bf16 v[22:25], v[162:165], v[152:155], v[22:25]
	v_and_b32_e32 v156, 0xc0, v146
	v_lshl_or_b32 v149, v149, 2, v156
	s_mov_b32 s12, 0
	v_mfma_f32_16x16x32_bf16 v[18:21], v[166:169], v[152:155], v[18:21]
	v_mfma_f32_16x16x32_bf16 v[14:17], v[170:173], v[152:155], v[14:17]
	ds_read_b128 v[152:155], v151
	ds_read_b128 v[198:201], v151 offset:2048
	ds_read_b128 v[202:205], v151 offset:4096
	ds_read_b128 v[206:209], v151 offset:6144
	s_waitcnt lgkmcnt(8)
	v_mfma_f32_16x16x32_bf16 v[10:13], v[142:145], v[174:177], v[10:13]
	ds_read_b128 v[142:145], v151 offset:8192
	ds_read_b128 v[210:213], v151 offset:10240
	ds_read_b128 v[214:217], v151 offset:12288
	ds_read_b128 v[218:221], v151 offset:14336
	s_waitcnt lgkmcnt(0)
	s_barrier
; DEV unsigned cvt_pk_bf16(float lo, float hi) { const f32x2_t v = {lo, hi}; const bf16x2_t b = __builtin_convertvector(v, bf16x2_t); return __builtin_bit_cast(unsigned, b); }
; template <class Epi>
; DEV void gemm256_tile(const bf16_t* __restrict__ A, int lda, const bf16_t* __restrict__ Bt, int ldb, int K, unsigned char* lds, const Epi& epi) {
;     ...
;                 for (int mi = 0; mi < 4; ++mi)
; #pragma unroll
;                     for (int ni = 0; ni < 4; ++ni) acc[mh * 4 + mi][ni] = __builtin_amdgcn_mfma_f32_16x16x32_bf16(bfr[ni], af[mi], acc[mh * 4 + mi][ni], 0, 0, 0);
;             }
;         }
;     }
;     ...
;     __syncthreads();
;     if constexpr (Epi::STAGE) {
; #pragma unroll
;         for (int mi = 0; mi < 8; ++mi)
; #pragma unroll
;             for (int ni = 0; ni < 4; ++ni) {
;                 const int row = wr * 128 + mi * 16 + fr, col = wc * 64 + ni * 16 + fq * 4;
;                 const f32x4 v = epi.xform(row, col, acc[mi][ni]);
;                 uint2 w; w.x = cvt_pk_bf16(v[0], v[1]); w.y = cvt_pk_bf16(v[2], v[3]);
;                 *(uint2*)(lds + row * 512 + ((((col >> 3) ^ (row & 31)) << 4) | (((col >> 2) & 1) << 3))) = w;
;             }
;         __syncthreads();
	v_mfma_f32_16x16x32_bf16 v[2:5], v[166:169], v[174:177], v[2:5]
	v_mfma_f32_16x16x32_bf16 v[126:129], v[182:185], v[152:155], v[126:129]
	v_mfma_f32_16x16x32_bf16 v[114:117], v[194:197], v[152:155], v[114:117]
	v_mfma_f32_16x16x32_bf16 v[102:105], v[190:193], v[198:201], v[102:105]
	s_nop 5
	v_cvt_pk_bf16_f32 v126, v126, v127
	v_cvt_pk_bf16_f32 v127, v128, v129
	v_lshrrev_b32_e32 v128, 3, v149
	v_mfma_f32_16x16x32_bf16 v[34:37], v[190:193], v[210:213], v[34:37]
	v_cvt_pk_bf16_f32 v114, v114, v115
	v_cvt_pk_bf16_f32 v115, v116, v117
	v_or_b32_e32 v117, 16, v147
	v_mfma_f32_16x16x32_bf16 v[2:5], v[190:193], v[218:221], v[2:5]
	v_cvt_pk_bf16_f32 v102, v102, v103
	v_cvt_pk_bf16_f32 v103, v104, v105
	v_bitop3_b32 v104, v128, v117, 4 bitop3:0x36
	v_mfma_f32_16x16x32_bf16 v[38:41], v[170:173], v[174:177], v[38:41]
	v_lshl_add_u32 v104, v104, 4, v148
	v_cvt_pk_bf16_f32 v34, v34, v35
	v_cvt_pk_bf16_f32 v35, v36, v37
	v_mfma_f32_16x16x32_bf16 v[6:9], v[162:165], v[174:177], v[6:9]
	v_cvt_pk_bf16_f32 v2, v2, v3
	v_cvt_pk_bf16_f32 v3, v4, v5
	ds_write2st64_b64 v104, v[34:35], v[2:3] offset0:80 offset1:112
	v_mfma_f32_16x16x32_bf16 v[30:33], v[194:197], v[210:213], v[30:33]
	v_xor_b32_e32 v129, v128, v147
	v_bitop3_b32 v116, v128, v147, 6 bitop3:0x36
	v_lshl_or_b32 v129, v129, 4, v148
	v_mfma_f32_16x16x32_bf16 v[98:101], v[194:197], v[198:201], v[98:101]
	v_lshl_add_u32 v116, v116, 4, v148
	s_nop 2
	v_cvt_pk_bf16_f32 v36, v30, v31
	v_cvt_pk_bf16_f32 v37, v32, v33
	v_mfma_f32_16x16x32_bf16 v[122:125], v[186:189], v[152:155], v[122:125]
	v_mfma_f32_16x16x32_bf16 v[118:121], v[190:193], v[152:155], v[118:121]
	v_cvt_pk_bf16_f32 v98, v98, v99
	v_cvt_pk_bf16_f32 v99, v100, v101
	v_bitop3_b32 v100, v128, v117, 6 bitop3:0x36
	v_mfma_f32_16x16x32_bf16 v[110:113], v[182:185], v[198:201], v[110:113]
	s_nop 2
	v_cvt_pk_bf16_f32 v122, v122, v123
	v_cvt_pk_bf16_f32 v123, v124, v125
	v_bitop3_b32 v124, v128, v147, 2 bitop3:0x36
	v_mfma_f32_16x16x32_bf16 v[106:109], v[186:189], v[198:201], v[106:109]
	v_cvt_pk_bf16_f32 v118, v118, v119
	v_cvt_pk_bf16_f32 v119, v120, v121
	v_bitop3_b32 v120, v128, v147, 4 bitop3:0x36
	v_mfma_f32_16x16x32_bf16 v[2:5], v[194:197], v[218:221], v[38:41]
	v_cvt_pk_bf16_f32 v110, v110, v111
	v_cvt_pk_bf16_f32 v111, v112, v113
	v_bitop3_b32 v112, v128, v147, 16 bitop3:0x1e
	v_mfma_f32_16x16x32_bf16 v[94:97], v[182:185], v[202:205], v[94:97]
	v_cvt_pk_bf16_f32 v106, v106, v107
	v_cvt_pk_bf16_f32 v107, v108, v109
	v_bitop3_b32 v108, v128, v117, 2 bitop3:0x36
	v_mfma_f32_16x16x32_bf16 v[90:93], v[186:189], v[202:205], v[90:93]
	v_lshl_add_u32 v100, v100, 4, v148
	v_cvt_pk_bf16_f32 v2, v2, v3
	v_cvt_pk_bf16_f32 v3, v4, v5
	v_mfma_f32_16x16x32_bf16 v[86:89], v[190:193], v[202:205], v[86:89]
	v_lshl_add_u32 v124, v124, 4, v148
	v_lshl_add_u32 v120, v120, 4, v148
	v_lshl_or_b32 v112, v112, 4, v148
	v_mfma_f32_16x16x32_bf16 v[82:85], v[194:197], v[202:205], v[82:85]
	v_lshl_add_u32 v108, v108, 4, v148
	v_cvt_pk_bf16_f32 v94, v94, v95
	v_cvt_pk_bf16_f32 v95, v96, v97
	v_mfma_f32_16x16x32_bf16 v[78:81], v[182:185], v[206:209], v[78:81]
	v_cvt_pk_bf16_f32 v90, v90, v91
	v_cvt_pk_bf16_f32 v91, v92, v93
	v_cvt_pk_bf16_f32 v86, v86, v87
	v_mfma_f32_16x16x32_bf16 v[74:77], v[186:189], v[206:209], v[74:77]
	v_cvt_pk_bf16_f32 v87, v88, v89
	v_cvt_pk_bf16_f32 v82, v82, v83
	v_cvt_pk_bf16_f32 v83, v84, v85
	v_mfma_f32_16x16x32_bf16 v[70:73], v[190:193], v[206:209], v[70:73]
	v_cvt_pk_bf16_f32 v78, v78, v79
	v_cvt_pk_bf16_f32 v79, v80, v81
	s_nop 1
	v_cvt_pk_bf16_f32 v74, v74, v75
	v_mfma_f32_16x16x32_bf16 v[66:69], v[194:197], v[206:209], v[66:69]
	v_cvt_pk_bf16_f32 v75, v76, v77
	s_nop 0
	v_cvt_pk_bf16_f32 v70, v70, v71
	v_cvt_pk_bf16_f32 v71, v72, v73
	v_mfma_f32_16x16x32_bf16 v[62:65], v[182:185], v[142:145], v[62:65]
	ds_write2st64_b64 v100, v[36:37], v[2:3] offset0:80 offset1:112
	s_nop 1
	v_cvt_pk_bf16_f32 v66, v66, v67
	v_cvt_pk_bf16_f32 v67, v68, v69
	v_mfma_f32_16x16x32_bf16 v[58:61], v[186:189], v[142:145], v[58:61]
	v_and_b32_e32 v2, 0x1f0, v140
	s_nop 0
	v_cvt_pk_bf16_f32 v62, v62, v63
	v_cvt_pk_bf16_f32 v63, v64, v65
	v_mfma_f32_16x16x32_bf16 v[54:57], v[190:193], v[142:145], v[54:57]
	ds_write2st64_b64 v129, v[126:127], v[94:95] offset1:32
	s_nop 1
	v_cvt_pk_bf16_f32 v58, v58, v59
	v_cvt_pk_bf16_f32 v59, v60, v61
	v_mfma_f32_16x16x32_bf16 v[50:53], v[194:197], v[142:145], v[50:53]
	ds_write2st64_b64 v124, v[122:123], v[90:91] offset1:32
	s_nop 0
	v_cvt_pk_bf16_f32 v54, v54, v55
	v_cvt_pk_bf16_f32 v55, v56, v57
	v_mfma_f32_16x16x32_bf16 v[46:49], v[182:185], v[210:213], v[46:49]
	ds_write2st64_b64 v120, v[118:119], v[86:87] offset1:32
	s_nop 1
	v_cvt_pk_bf16_f32 v50, v50, v51
	v_cvt_pk_bf16_f32 v51, v52, v53
	v_mfma_f32_16x16x32_bf16 v[42:45], v[186:189], v[210:213], v[42:45]
	ds_write2st64_b64 v116, v[114:115], v[82:83] offset1:32
	s_nop 0
	v_cvt_pk_bf16_f32 v46, v46, v47
	v_cvt_pk_bf16_f32 v47, v48, v49
	v_mfma_f32_16x16x32_bf16 v[30:33], v[182:185], v[214:217], v[178:181]
	ds_write2st64_b64 v112, v[110:111], v[78:79] offset0:16 offset1:48
	s_nop 1
	v_cvt_pk_bf16_f32 v42, v42, v43
	v_cvt_pk_bf16_f32 v43, v44, v45
	v_mfma_f32_16x16x32_bf16 v[22:25], v[186:189], v[214:217], v[22:25]
	ds_write2st64_b64 v108, v[106:107], v[74:75] offset0:16 offset1:48
	s_nop 0
	v_cvt_pk_bf16_f32 v30, v30, v31
	v_cvt_pk_bf16_f32 v31, v32, v33
	v_mfma_f32_16x16x32_bf16 v[18:21], v[190:193], v[214:217], v[18:21]
	ds_write2st64_b64 v104, v[102:103], v[70:71] offset0:16 offset1:48
	s_nop 1
	v_cvt_pk_bf16_f32 v22, v22, v23
	v_cvt_pk_bf16_f32 v23, v24, v25
	v_mfma_f32_16x16x32_bf16 v[14:17], v[194:197], v[214:217], v[14:17]
	ds_write2st64_b64 v100, v[98:99], v[66:67] offset0:16 offset1:48
	s_nop 0
	v_cvt_pk_bf16_f32 v18, v18, v19
	v_cvt_pk_bf16_f32 v19, v20, v21
	v_mfma_f32_16x16x32_bf16 v[10:13], v[182:185], v[218:221], v[10:13]
	ds_write2st64_b64 v129, v[62:63], v[30:31] offset0:64 offset1:96
	s_nop 1
	v_cvt_pk_bf16_f32 v14, v14, v15
	v_cvt_pk_bf16_f32 v15, v16, v17
	v_mfma_f32_16x16x32_bf16 v[6:9], v[186:189], v[218:221], v[6:9]
	ds_write2st64_b64 v124, v[58:59], v[22:23] offset0:64 offset1:96
	s_nop 0
	v_cvt_pk_bf16_f32 v10, v10, v11
	v_cvt_pk_bf16_f32 v11, v12, v13
	ds_write2st64_b64 v120, v[54:55], v[18:19] offset0:64 offset1:96
	ds_write2st64_b64 v116, v[50:51], v[14:15] offset0:64 offset1:96
	s_nop 1
	v_cvt_pk_bf16_f32 v6, v6, v7
	v_cvt_pk_bf16_f32 v7, v8, v9
	ds_write2st64_b64 v112, v[46:47], v[10:11] offset0:80 offset1:112
	ds_write2st64_b64 v108, v[42:43], v[6:7] offset0:80 offset1:112
	s_waitcnt lgkmcnt(0)
	s_barrier
